# adds: branch outputs y stored block-permuted (16B per lane per dt pair, dwordx4 stores) with w_out rows permuted identically in P0
# speedup vs baseline: 1.0013x; 1.0013x over previous
; #define LAS __attribute__((address_space(3)))
; __device__ __forceinline__ void transpose_item(const float* W, int ldw, int K, int ncols, bf16_t* WT, int row_off, LAS float* scr, int item, int lane) {
;     const int nblk = ncols / 64, kb = item / nblk, nb = item % nblk, k0 = 64 * kb, n0 = 64 * nb;
;     f32x4 v[16];
; #pragma unroll
;     for (int i = 0; i < 16; ++i) v[i] = *(const f32x4*)(W + (size_t)(k0 + 4 * i + (lane >> 4)) * ldw + n0 + (lane & 15) * 4);
; #pragma unroll
;     for (int i = 0; i < 16; ++i) { LAS float* d = scr + (4 * i + (lane >> 4)) * 65 + (lane & 15) * 4; d[0] = v[i].x; d[1] = v[i].y; d[2] = v[i].z; d[3] = v[i].w; }
; __device__ __forceinline__ void p0_phase(const Args& a, LAS unsigned char* lds) {
;     ...
;         else if (r < 1664) { r -= 1280; transpose_item(a.w_out + (size_t)l * DMIX * DM, DM, DMIX, DM, WoutT + (size_t)l * DM * DMIX, 0, scr, r, lane); }
.LBB0_14:
	s_andn2_saveexec_b64 s[20:21], s[20:21]
	s_cbranch_execz .LBB0_16
	v_lshlrev_b16_e32 v4, 2, v7
	v_and_b32_e32 v4, 0x1fc0, v4
	v_add_u16_e32 v9, 0xec00, v4
	v_lshlrev_b16_e32 v4, 6, v7
	v_mul_hi_i32_i24_e32 v57, 0x600000, v10
	v_mul_i32_i24_e32 v56, 0x600000, v10
	v_and_b32_e32 v55, 0x3c0, v4
	v_lshl_add_u64 v[56:57], s[90:91], 0, v[56:57]
	v_lshlrev_b32_sdwa v4, v54, v55 dst_sel:DWORD dst_unused:UNUSED_PAD src0_sel:DWORD src1_sel:WORD_0
	v_or_b32_e32 v11, v3, v9
	v_lshl_add_u64 v[56:57], v[56:57], 0, v[4:5]
	v_mov_b32_e32 v7, v5
	v_lshl_add_u64 v[56:57], v[56:57], 0, v[6:7]
	v_lshlrev_b32_e32 v4, 12, v11
	v_lshl_add_u64 v[116:117], v[56:57], 0, v[4:5]
	v_add_co_u32_e32 v60, vcc, s28, v116
	v_mul_hi_i32_i24_e32 v11, 0x300000, v10
	s_nop 0
	v_addc_co_u32_e32 v61, vcc, 0, v117, vcc
	v_add_co_u32_e32 v64, vcc, s25, v116
	global_load_dwordx4 v[56:59], v[116:117], off
	s_nop 0
	global_load_dwordx4 v[60:63], v[60:61], off
	v_addc_co_u32_e32 v65, vcc, 0, v117, vcc
	v_add_co_u32_e32 v68, vcc, s29, v116
	v_mul_i32_i24_e32 v10, 0x300000, v10
	s_nop 0
	v_addc_co_u32_e32 v69, vcc, 0, v117, vcc
	v_add_co_u32_e32 v72, vcc, s26, v116
	global_load_dwordx4 v[64:67], v[64:65], off
	s_nop 0
	global_load_dwordx4 v[68:71], v[68:69], off
	v_addc_co_u32_e32 v73, vcc, 0, v117, vcc
	v_add_co_u32_e32 v76, vcc, s33, v116
	v_lshl_add_u64 v[10:11], s[6:7], 0, v[10:11]
	s_nop 0
	v_addc_co_u32_e32 v77, vcc, 0, v117, vcc
	v_add_co_u32_e32 v80, vcc, s27, v116
	global_load_dwordx4 v[72:75], v[72:73], off
	s_nop 0
	global_load_dwordx4 v[76:79], v[76:77], off
	v_addc_co_u32_e32 v81, vcc, 0, v117, vcc
	v_add_co_u32_e32 v84, vcc, s34, v116
	v_lshlrev_b32_e32 v4, 1, v9
	s_nop 0
	v_addc_co_u32_e32 v85, vcc, 0, v117, vcc
	v_add_co_u32_e32 v88, vcc, s35, v116
	global_load_dwordx4 v[80:83], v[80:81], off
	s_nop 0
	global_load_dwordx4 v[84:87], v[84:85], off
	v_addc_co_u32_e32 v89, vcc, 0, v117, vcc
	v_add_co_u32_e32 v92, vcc, s39, v116
	v_lshl_add_u64 v[10:11], v[10:11], 0, v[4:5]
	s_nop 0
	v_addc_co_u32_e32 v93, vcc, 0, v117, vcc
	v_add_co_u32_e32 v96, vcc, s36, v116
	global_load_dwordx4 v[88:91], v[88:89], off
	s_nop 0
	global_load_dwordx4 v[92:95], v[92:93], off
	v_addc_co_u32_e32 v97, vcc, 0, v117, vcc
	v_add_co_u32_e32 v100, vcc, s40, v116
	v_or_b32_sdwa v4, v13, v55 dst_sel:DWORD dst_unused:UNUSED_PAD src0_sel:DWORD src1_sel:WORD_0
	s_nop 0
	v_addc_co_u32_e32 v101, vcc, 0, v117, vcc
	v_add_co_u32_e32 v104, vcc, s37, v116
	global_load_dwordx4 v[96:99], v[96:97], off
	s_nop 0
	global_load_dwordx4 v[100:103], v[100:101], off
	v_addc_co_u32_e32 v105, vcc, 0, v117, vcc
	v_add_co_u32_e32 v108, vcc, s41, v116
	v_mov_b32_e32 v9, v5
	s_nop 0
	v_addc_co_u32_e32 v109, vcc, 0, v117, vcc
	global_load_dwordx4 v[104:107], v[104:105], off
	s_nop 0
	global_load_dwordx4 v[108:111], v[108:109], off
	v_add_co_u32_e32 v112, vcc, s38, v116
	v_mul_u32_u24_e32 v4, 0x600, v4
	s_nop 0
	v_addc_co_u32_e32 v113, vcc, 0, v117, vcc
	global_load_dwordx4 v[112:115], v[112:113], off
	v_add_co_u32_e32 v116, vcc, s42, v116
	v_lshl_add_u64 v[10:11], v[10:11], 0, v[8:9]
	s_nop 0
	v_addc_co_u32_e32 v117, vcc, 0, v117, vcc
	global_load_dwordx4 v[116:119], v[116:117], off
	v_lshlrev_b32_e32 v4, 1, v4
	s_waitcnt vmcnt(15)
	ds_write2_b32 v12, v56, v57 offset1:1
	ds_write2_b32 v12, v58, v59 offset0:2 offset1:3
	s_waitcnt vmcnt(14)
	ds_write2_b32 v22, v60, v61 offset1:1
	ds_write2_b32 v23, v62, v63 offset1:1
	s_waitcnt vmcnt(13)
	ds_write2_b32 v24, v64, v65 offset1:1
	ds_write2_b32 v25, v66, v67 offset1:1
	s_waitcnt vmcnt(12)
	ds_write2_b32 v26, v68, v69 offset1:1
	ds_write2_b32 v27, v70, v71 offset1:1
	s_waitcnt vmcnt(11)
	ds_write2_b32 v28, v72, v73 offset1:1
	ds_write2_b32 v29, v74, v75 offset1:1
	s_waitcnt vmcnt(10)
	ds_write2_b32 v30, v76, v77 offset1:1
	ds_write2_b32 v31, v78, v79 offset1:1
	s_waitcnt vmcnt(9)
	ds_write2_b32 v32, v80, v81 offset1:1
	ds_write2_b32 v33, v82, v83 offset1:1
	s_waitcnt vmcnt(8)
	ds_write2_b32 v34, v84, v85 offset1:1
	ds_write2_b32 v35, v86, v87 offset1:1
	s_waitcnt vmcnt(7)
	ds_write2_b32 v36, v88, v89 offset1:1
	ds_write2_b32 v37, v90, v91 offset1:1
	s_waitcnt vmcnt(6)
	ds_write2_b32 v38, v92, v93 offset1:1
	ds_write2_b32 v39, v94, v95 offset1:1
	s_waitcnt vmcnt(5)
	ds_write2_b32 v40, v96, v97 offset1:1
	ds_write2_b32 v41, v98, v99 offset1:1
	s_waitcnt vmcnt(4)
	ds_write2_b32 v42, v100, v101 offset1:1
	ds_write2_b32 v43, v102, v103 offset1:1
	s_waitcnt vmcnt(3)
	ds_write2_b32 v44, v104, v105 offset1:1
	ds_write2_b32 v45, v106, v107 offset1:1
	s_waitcnt vmcnt(2)
	ds_write2_b32 v46, v108, v109 offset1:1
	ds_write2_b32 v47, v110, v111 offset1:1
	s_waitcnt vmcnt(1)
	ds_write2_b32 v48, v112, v113 offset1:1
	ds_write2_b32 v49, v114, v115 offset1:1
	s_waitcnt vmcnt(0)
	ds_write2_b32 v50, v116, v117 offset1:1
	ds_write2_b32 v51, v118, v119 offset1:1
	s_waitcnt lgkmcnt(0)
; #define LAS __attribute__((address_space(3)))
; __device__ __forceinline__ unsigned pk2(float lo, float hi) { f32x2_t v = {lo, hi}; bf16x2_t b = __builtin_convertvector(v, bf16x2_t); return __builtin_bit_cast(unsigned, b); }
; #define LDS_WAIT() asm volatile("s_waitcnt lgkmcnt(0)" ::: "memory")
; __device__ __forceinline__ void transpose_item(const float* W, int ldw, int K, int ncols, bf16_t* WT, int row_off, LAS float* scr, int item, int lane) {
;     ...
;     LDS_WAIT();
;     const int c = lane & 7;
; #pragma unroll
;     for (int j = 0; j < 8; ++j) { const int n = (lane >> 3) + 8 * j; const LAS float* s = scr + (8 * c) * 65 + n;
;         u32x4 o; o.x = pk2(s[0 * 65], s[1 * 65]); o.y = pk2(s[2 * 65], s[3 * 65]); o.z = pk2(s[4 * 65], s[5 * 65]); o.w = pk2(s[6 * 65], s[7 * 65]);
;         *(u32x4*)(WT + (size_t)(row_off + n0 + n) * K + k0 + 8 * c) = o; }
;     LDS_WAIT();
	ds_read2_b32 v[60:61], v14 offset0:65 offset1:73
	ds_read2_b32 v[62:63], v14 offset1:8
	ds_read2_b32 v[64:65], v14 offset0:130 offset1:138
	ds_read2_b32 v[66:67], v14 offset0:195 offset1:203
	ds_read2_b32 v[68:69], v53 offset0:4 offset1:12
	ds_read2_b32 v[70:71], v53 offset0:69 offset1:77
	ds_read2_b32 v[72:73], v53 offset0:134 offset1:142
	ds_read2_b32 v[74:75], v53 offset0:199 offset1:207
	v_lshl_add_u64 v[76:77], v[10:11], 0, v[4:5]
	v_or_b32_sdwa v4, v15, v55 dst_sel:DWORD dst_unused:UNUSED_PAD src0_sel:DWORD src1_sel:WORD_0
	v_mul_u32_u24_e32 v4, 0x600, v4
	s_waitcnt lgkmcnt(6)
	v_cvt_pk_bf16_f32 v56, v62, v60
	s_waitcnt lgkmcnt(4)
	v_cvt_pk_bf16_f32 v57, v64, v66
	s_waitcnt lgkmcnt(2)
	v_cvt_pk_bf16_f32 v58, v68, v70
	s_waitcnt lgkmcnt(0)
	v_cvt_pk_bf16_f32 v59, v72, v74
	v_lshlrev_b32_e32 v4, 1, v4
	global_store_dwordx4 v[76:77], v[56:59], off
	s_nop 1
	v_cvt_pk_bf16_f32 v56, v63, v61
	v_cvt_pk_bf16_f32 v57, v65, v67
	v_cvt_pk_bf16_f32 v58, v69, v71
	v_cvt_pk_bf16_f32 v59, v73, v75
	v_lshl_add_u64 v[60:61], v[10:11], 0, v[4:5]
	global_store_dwordx4 v[60:61], v[56:59], off
	ds_read2_b32 v[60:61], v14 offset0:16 offset1:24
	ds_read2_b32 v[62:63], v14 offset0:81 offset1:89
	ds_read2_b32 v[64:65], v14 offset0:146 offset1:154
	ds_read2_b32 v[66:67], v14 offset0:211 offset1:219
	ds_read2_b32 v[68:69], v53 offset0:20 offset1:28
	ds_read2_b32 v[70:71], v53 offset0:85 offset1:93
	v_or_b32_sdwa v4, v16, v55 dst_sel:DWORD dst_unused:UNUSED_PAD src0_sel:DWORD src1_sel:WORD_0
	ds_read2_b32 v[72:73], v53 offset0:150 offset1:158
	ds_read2_b32 v[74:75], v53 offset0:215 offset1:223
	v_mul_u32_u24_e32 v4, 0x600, v4
	v_lshlrev_b32_e32 v4, 1, v4
	v_lshl_add_u64 v[76:77], v[10:11], 0, v[4:5]
	v_or_b32_sdwa v4, v17, v55 dst_sel:DWORD dst_unused:UNUSED_PAD src0_sel:DWORD src1_sel:WORD_0
	v_mul_u32_u24_e32 v4, 0x600, v4
	s_waitcnt lgkmcnt(6)
	v_cvt_pk_bf16_f32 v56, v60, v62
	s_waitcnt lgkmcnt(4)
	v_cvt_pk_bf16_f32 v57, v64, v66
	s_waitcnt lgkmcnt(2)
	v_cvt_pk_bf16_f32 v58, v68, v70
	s_waitcnt lgkmcnt(0)
	v_cvt_pk_bf16_f32 v59, v72, v74
	v_lshlrev_b32_e32 v4, 1, v4
	global_store_dwordx4 v[76:77], v[56:59], off
	s_nop 1
	v_cvt_pk_bf16_f32 v56, v61, v63
	v_cvt_pk_bf16_f32 v57, v65, v67
	v_cvt_pk_bf16_f32 v58, v69, v71
	v_cvt_pk_bf16_f32 v59, v73, v75
	v_lshl_add_u64 v[60:61], v[10:11], 0, v[4:5]
	global_store_dwordx4 v[60:61], v[56:59], off
	ds_read2_b32 v[60:61], v14 offset0:32 offset1:40
	ds_read2_b32 v[62:63], v14 offset0:97 offset1:105
	ds_read2_b32 v[64:65], v14 offset0:162 offset1:170
	ds_read2_b32 v[66:67], v14 offset0:227 offset1:235
	ds_read2_b32 v[68:69], v53 offset0:36 offset1:44
	ds_read2_b32 v[70:71], v53 offset0:101 offset1:109
	v_or_b32_sdwa v4, v18, v55 dst_sel:DWORD dst_unused:UNUSED_PAD src0_sel:DWORD src1_sel:WORD_0
	ds_read2_b32 v[72:73], v53 offset0:166 offset1:174
	ds_read2_b32 v[74:75], v53 offset0:231 offset1:239
	v_mul_u32_u24_e32 v4, 0x600, v4
	v_lshlrev_b32_e32 v4, 1, v4
	v_lshl_add_u64 v[76:77], v[10:11], 0, v[4:5]
	v_or_b32_sdwa v4, v19, v55 dst_sel:DWORD dst_unused:UNUSED_PAD src0_sel:DWORD src1_sel:WORD_0
	v_mul_u32_u24_e32 v4, 0x600, v4
	s_waitcnt lgkmcnt(6)
	v_cvt_pk_bf16_f32 v56, v60, v62
	s_waitcnt lgkmcnt(4)
	v_cvt_pk_bf16_f32 v57, v64, v66
	s_waitcnt lgkmcnt(2)
	v_cvt_pk_bf16_f32 v58, v68, v70
	s_waitcnt lgkmcnt(0)
	v_cvt_pk_bf16_f32 v59, v72, v74
	v_lshlrev_b32_e32 v4, 1, v4
	global_store_dwordx4 v[76:77], v[56:59], off
	s_nop 1
	v_cvt_pk_bf16_f32 v56, v61, v63
	v_cvt_pk_bf16_f32 v57, v65, v67
	v_cvt_pk_bf16_f32 v58, v69, v71
	v_cvt_pk_bf16_f32 v59, v73, v75
	v_lshl_add_u64 v[60:61], v[10:11], 0, v[4:5]
	global_store_dwordx4 v[60:61], v[56:59], off
	ds_read2_b32 v[60:61], v14 offset0:48 offset1:56
	ds_read2_b32 v[62:63], v14 offset0:113 offset1:121
	ds_read2_b32 v[64:65], v14 offset0:178 offset1:186
	ds_read2_b32 v[66:67], v14 offset0:243 offset1:251
	ds_read2_b32 v[68:69], v53 offset0:52 offset1:60
	ds_read2_b32 v[70:71], v53 offset0:117 offset1:125
	v_or_b32_sdwa v4, v20, v55 dst_sel:DWORD dst_unused:UNUSED_PAD src0_sel:DWORD src1_sel:WORD_0
	ds_read2_b32 v[72:73], v53 offset0:182 offset1:190
	ds_read2_b32 v[74:75], v53 offset0:247 offset1:255
	v_mul_u32_u24_e32 v4, 0x600, v4
	v_lshlrev_b32_e32 v4, 1, v4
	v_lshl_add_u64 v[76:77], v[10:11], 0, v[4:5]
	v_or_b32_sdwa v4, v21, v55 dst_sel:DWORD dst_unused:UNUSED_PAD src0_sel:DWORD src1_sel:WORD_0
	v_mul_u32_u24_e32 v4, 0x600, v4
	s_waitcnt lgkmcnt(6)
	v_cvt_pk_bf16_f32 v56, v60, v62
	s_waitcnt lgkmcnt(4)
	v_cvt_pk_bf16_f32 v57, v64, v66
	s_waitcnt lgkmcnt(2)
	v_cvt_pk_bf16_f32 v58, v68, v70
	s_waitcnt lgkmcnt(0)
	v_cvt_pk_bf16_f32 v59, v72, v74
	v_lshlrev_b32_e32 v4, 1, v4
	global_store_dwordx4 v[76:77], v[56:59], off
	v_lshl_add_u64 v[10:11], v[10:11], 0, v[4:5]
	s_nop 0
	v_cvt_pk_bf16_f32 v56, v61, v63
	v_cvt_pk_bf16_f32 v57, v65, v67
	v_cvt_pk_bf16_f32 v58, v69, v71
	v_cvt_pk_bf16_f32 v59, v73, v75
	global_store_dwordx4 v[10:11], v[56:59], off
	s_waitcnt lgkmcnt(0)

; #define LAS __attribute__((address_space(3)))
; template <int D, int QT0>
; __device__ __forceinline__ void qk_tile(const LAS unsigned char* Ks, int KP, const bf16x8 (&qf)[2][D / 32], f32x4 (&s)[4][2], int fr, int fq, float b0, float b1) {
; #pragma unroll
;     for (int a = 0; a < 4; ++a) { s[a][0] = (f32x4){b0, b0, b0, b0}; s[a][1] = (f32x4){b1, b1, b1, b1}; }
; #pragma unroll
;     for (int a = 0; a < 4; ++a)
; #pragma unroll
;         for (int ks = 0; ks < D / 32; ++ks) { const bf16x8 kfr = *(const LAS bf16x8*)(Ks + (a * 16 + fr) * KP + (ks * 32 + fq * 8) * 2);
;             if (QT0 == 0) s[a][0] = MFMA16(kfr, qf[0][ks], s[a][0]);
;             s[a][1] = MFMA16(kfr, qf[1][ks], s[a][1]); }
; }
; template <int D, bool DIAG, int QT0>
; __device__ __forceinline__ void sm_pv_tile(f32x4 (&s)[4][2], const LAS unsigned char* Vs, int VP, f32x4 (&o)[D / 16][2], f32x4 (&ol)[2], int fr, int fq, int keyl0, int qla, int qlb) {
; #pragma unroll
;     for (int qt = QT0; qt < 2; ++qt) {
;         if (DIAG) {
;             const int ql = (qt == 0 ? qla : qlb) + fr - keyl0 - fq * 4;
; #pragma unroll
;             for (int a = 0; a < 4; ++a)
; #pragma unroll
;                 for (int jj = 0; jj < 4; ++jj) s[a][qt][jj] = (a * 16 + jj > ql) ? -1e30f : s[a][qt][jj];
;         }
; #pragma unroll
;         for (int a = 0; a < 4; ++a)
; #pragma unroll
;             for (int jj = 0; jj < 4; ++jj) s[a][qt][jj] = ex2(s[a][qt][jj]);
;     }
; #pragma unroll
;     for (int kst = 0; kst < 2; ++kst) {
;         bf16x8 pb[2];
; #pragma unroll
;         for (int qt = QT0; qt < 2; ++qt) { u32x4 pw; pw.x = pk2(s[2 * kst][qt][0], s[2 * kst][qt][1]); pw.y = pk2(s[2 * kst][qt][2], s[2 * kst][qt][3]);
;             pw.z = pk2(s[2 * kst + 1][qt][0], s[2 * kst + 1][qt][1]); pw.w = pk2(s[2 * kst + 1][qt][2], s[2 * kst + 1][qt][3]); pb[qt] = __builtin_bit_cast(bf16x8, pw); }
;         if (QT0 == 0) ol[0] = MFMA16(ONES8, pb[0], ol[0]);
;         ol[1] = MFMA16(ONES8, pb[1], ol[1]);
; #pragma unroll
;         for (int dt = 0; dt < D / 16; ++dt) { const s16x4 lo = tr4(Vs, VP, kst * 32 + fq * 4, dt * 16, fr), hi = tr4(Vs, VP, kst * 32 + 16 + fq * 4, dt * 16, fr);
;             const bf16x8 vf = __builtin_shufflevector(lo, hi, 0, 1, 2, 3, 4, 5, 6, 7);
;             if (QT0 == 0) o[dt][0] = MFMA16(vf, pb[0], o[dt][0]);
;             o[dt][1] = MFMA16(vf, pb[1], o[dt][1]); }
;     }
.LBB0_520:
	v_lshl_add_u64 v[116:117], v[166:167], 0, s[46:47]
	v_add_co_u32_e32 v116, vcc, s34, v116
	s_bitcmp1_b32 s6, 0
	s_nop 0
	v_addc_co_u32_e32 v117, vcc, 0, v117, vcc
	global_load_dwordx4 v[128:131], v[116:117], off
	global_load_dwordx4 v[124:127], v[116:117], off offset:1024
	v_lshl_add_u64 v[116:117], v[164:165], 0, s[46:47]
	v_add_co_u32_e32 v116, vcc, s34, v116
	s_cselect_b32 s4, 0x8c00, 0
	s_nop 0
	v_addc_co_u32_e32 v117, vcc, 0, v117, vcc
	v_add_u32_e32 v181, s4, v176
	global_load_dwordx4 v[120:123], v[116:117], off
	s_nop 0
	global_load_dwordx4 v[116:119], v[116:117], off offset:1024
	ds_read_b128 v[132:135], v181
	ds_read_b128 v[140:143], v181 offset:64
	s_waitcnt lgkmcnt(1)
	v_mfma_f32_16x16x32_bf16 v[136:139], v[132:135], v[16:19], v[72:75]
	ds_read_b128 v[204:207], v181 offset:4416
	s_mov_b32 s70, s68
	s_mov_b32 s71, s68
	v_mfma_f32_16x16x32_bf16 v[132:135], v[132:135], v[24:27], v[72:75]
	ds_read_b128 v[212:215], v181 offset:8768
	s_mov_b32 s69, s68
	ds_read_b128 v[220:223], v181 offset:13120
	s_waitcnt lgkmcnt(3)
	v_mfma_f32_16x16x32_bf16 v[136:139], v[140:143], v[20:23], v[136:139]
	v_mfma_f32_16x16x32_bf16 v[132:135], v[140:143], v[28:31], v[132:135]
	ds_read_b128 v[140:143], v181 offset:128
	s_waitcnt lgkmcnt(0)
	v_mfma_f32_16x16x32_bf16 v[136:139], v[140:143], v[12:15], v[136:139]
	v_mfma_f32_16x16x32_bf16 v[132:135], v[140:143], v[36:39], v[132:135]
	ds_read_b128 v[140:143], v181 offset:192
	s_waitcnt lgkmcnt(0)
	v_mfma_f32_16x16x32_bf16 v[136:139], v[140:143], v[8:11], v[136:139]
	s_nop 7
	v_exp_f32_e32 v136, v136
	v_mfma_f32_16x16x32_bf16 v[132:135], v[140:143], v[32:35], v[132:135]
	ds_read_b128 v[140:143], v181 offset:4352
	v_exp_f32_e32 v137, v137
	v_exp_f32_e32 v138, v138
	s_waitcnt lgkmcnt(0)
	v_mfma_f32_16x16x32_bf16 v[200:203], v[140:143], v[16:19], v[72:75]
	v_exp_f32_e32 v139, v139
	v_mfma_f32_16x16x32_bf16 v[140:143], v[140:143], v[24:27], v[72:75]
	v_mfma_f32_16x16x32_bf16 v[200:203], v[204:207], v[20:23], v[200:203]
	v_mfma_f32_16x16x32_bf16 v[140:143], v[204:207], v[28:31], v[140:143]
	ds_read_b128 v[204:207], v181 offset:4480
	s_waitcnt lgkmcnt(0)
	v_mfma_f32_16x16x32_bf16 v[200:203], v[204:207], v[12:15], v[200:203]
	v_mfma_f32_16x16x32_bf16 v[140:143], v[204:207], v[36:39], v[140:143]
	ds_read_b128 v[204:207], v181 offset:4544
	s_waitcnt lgkmcnt(0)
	v_mfma_f32_16x16x32_bf16 v[200:203], v[204:207], v[8:11], v[200:203]
	s_nop 7
	v_exp_f32_e32 v225, v201
	v_mfma_f32_16x16x32_bf16 v[140:143], v[204:207], v[32:35], v[140:143]
	ds_read_b128 v[204:207], v181 offset:8704
	v_exp_f32_e32 v226, v202
	v_exp_f32_e32 v227, v203
	s_waitcnt lgkmcnt(0)
	v_mfma_f32_16x16x32_bf16 v[208:211], v[204:207], v[16:19], v[72:75]
	v_exp_f32_e32 v224, v200
	s_nop 1
	v_exp_f32_e32 v140, v140
	v_exp_f32_e32 v141, v141
	v_mfma_f32_16x16x32_bf16 v[204:207], v[204:207], v[24:27], v[72:75]
	v_exp_f32_e32 v142, v142
	v_exp_f32_e32 v143, v143
	v_mfma_f32_16x16x32_bf16 v[208:211], v[212:215], v[20:23], v[208:211]
	v_mfma_f32_16x16x32_bf16 v[204:207], v[212:215], v[28:31], v[204:207]
	ds_read_b128 v[212:215], v181 offset:8832
	s_waitcnt lgkmcnt(0)
	v_mfma_f32_16x16x32_bf16 v[208:211], v[212:215], v[12:15], v[208:211]
	v_mfma_f32_16x16x32_bf16 v[204:207], v[212:215], v[36:39], v[204:207]
	ds_read_b128 v[212:215], v181 offset:8896
	s_waitcnt lgkmcnt(0)
	v_mfma_f32_16x16x32_bf16 v[208:211], v[212:215], v[8:11], v[208:211]
	s_nop 7
	v_exp_f32_e32 v200, v211
	v_mfma_f32_16x16x32_bf16 v[212:215], v[212:215], v[32:35], v[204:207]
	v_exp_f32_e32 v182, v209
	v_exp_f32_e32 v183, v210
	s_nop 0
	ds_read_b128 v[204:207], v181 offset:13056
	s_waitcnt lgkmcnt(0)
	v_mfma_f32_16x16x32_bf16 v[216:219], v[204:207], v[16:19], v[72:75]
	v_mfma_f32_16x16x32_bf16 v[204:207], v[204:207], v[24:27], v[72:75]
	v_mfma_f32_16x16x32_bf16 v[216:219], v[220:223], v[20:23], v[216:219]
	v_mfma_f32_16x16x32_bf16 v[204:207], v[220:223], v[28:31], v[204:207]
	ds_read_b128 v[220:223], v181 offset:13184
	s_waitcnt lgkmcnt(0)
	v_mfma_f32_16x16x32_bf16 v[216:219], v[220:223], v[12:15], v[216:219]
	v_mfma_f32_16x16x32_bf16 v[204:207], v[220:223], v[36:39], v[204:207]
	ds_read_b128 v[220:223], v181 offset:13248
	v_exp_f32_e32 v181, v208
	v_exp_f32_e32 v208, v215
	s_waitcnt lgkmcnt(0)
	v_mfma_f32_16x16x32_bf16 v[216:219], v[220:223], v[8:11], v[216:219]
	s_nop 7
	v_exp_f32_e32 v201, v216
	v_mfma_f32_16x16x32_bf16 v[220:223], v[220:223], v[32:35], v[204:207]
	v_exp_f32_e32 v202, v217
	v_exp_f32_e32 v203, v218
	v_exp_f32_e32 v216, v132
	v_exp_f32_e32 v204, v219
	v_exp_f32_e32 v217, v133
	v_exp_f32_e32 v218, v134
	v_exp_f32_e32 v219, v135
	v_exp_f32_e32 v206, v213
	v_add_u32_e32 v213, s4, v172
	v_exp_f32_e32 v211, v222
	v_add_u32_e32 v222, v213, v170
	v_exp_f32_e32 v207, v214
	v_exp_f32_e32 v209, v220
	v_exp_f32_e32 v210, v221
	v_cvt_pk_bf16_f32 v132, v136, v137
	v_cvt_pk_bf16_f32 v136, v216, v217
	v_cvt_pk_bf16_f32 v137, v218, v219
	ds_read_b64_tr_b16 v[216:217], v222 offset:22016
	ds_read_b64_tr_b16 v[214:215], v222 offset:17408
	ds_read_b64_tr_b16 v[218:219], v222 offset:17440
	ds_read_b64_tr_b16 v[220:221], v222 offset:22048
	v_cvt_pk_bf16_f32 v133, v138, v139
	v_cvt_pk_bf16_f32 v134, v224, v225
	v_cvt_pk_bf16_f32 v135, v226, v227
	v_cvt_pk_bf16_f32 v138, v140, v141
	v_cvt_pk_bf16_f32 v139, v142, v143
	s_waitcnt lgkmcnt(2)
	v_mfma_f32_16x16x32_bf16 v[84:87], v[214:217], v[132:135], v[84:87]
	v_mov_b64_e32 v[142:143], s[70:71]
	v_mov_b64_e32 v[140:141], s[68:69]
	v_exp_f32_e32 v205, v212
	v_mfma_f32_16x16x32_bf16 v[88:91], v[214:217], v[136:139], v[88:91]
	ds_read_b64_tr_b16 v[214:215], v222 offset:17472
	ds_read_b64_tr_b16 v[216:217], v222 offset:22080
	v_exp_f32_e32 v212, v223
	s_andn2_b32 s4, 1, s6
	s_waitcnt lgkmcnt(2)
; __device__ __forceinline__ unsigned pk2(float lo, float hi) { f32x2_t v = {lo, hi}; bf16x2_t b = __builtin_convertvector(v, bf16x2_t); return __builtin_bit_cast(unsigned, b); }
; #define MFMA16(a, b, c) __builtin_amdgcn_mfma_f32_16x16x32_bf16((a), (b), (c), 0, 0, 0)
; template <int D, bool DIAG, int QT0>
; __device__ __forceinline__ void sm_pv_tile(f32x4 (&s)[4][2], const LAS unsigned char* Vs, int VP, f32x4 (&o)[D / 16][2], f32x4 (&ol)[2], int fr, int fq, int keyl0, int qla, int qlb) {
;     ...
;     for (int kst = 0; kst < 2; ++kst) {
;         bf16x8 pb[2];
; #pragma unroll
;         for (int qt = QT0; qt < 2; ++qt) { u32x4 pw; pw.x = pk2(s[2 * kst][qt][0], s[2 * kst][qt][1]); pw.y = pk2(s[2 * kst][qt][2], s[2 * kst][qt][3]);
;             pw.z = pk2(s[2 * kst + 1][qt][0], s[2 * kst + 1][qt][1]); pw.w = pk2(s[2 * kst + 1][qt][2], s[2 * kst + 1][qt][3]); pb[qt] = __builtin_bit_cast(bf16x8, pw); }
;         if (QT0 == 0) ol[0] = MFMA16(ONES8, pb[0], ol[0]);
;         ol[1] = MFMA16(ONES8, pb[1], ol[1]);
; #pragma unroll
;         for (int dt = 0; dt < D / 16; ++dt) { const s16x4 lo = tr4(Vs, VP, kst * 32 + fq * 4, dt * 16, fr), hi = tr4(Vs, VP, kst * 32 + 16 + fq * 4, dt * 16, fr);
;             const bf16x8 vf = __builtin_shufflevector(lo, hi, 0, 1, 2, 3, 4, 5, 6, 7);
;             if (QT0 == 0) o[dt][0] = MFMA16(vf, pb[0], o[dt][0]);
;             o[dt][1] = MFMA16(vf, pb[1], o[dt][1]); }
;     }
	v_mfma_f32_16x16x32_bf16 v[92:95], v[218:221], v[132:135], v[92:95]
	s_mul_i32 s4, s4, 0x8c00
	s_add_i32 s6, s6, 1
	s_add_u32 s46, s46, 0x20000
	v_mfma_f32_16x16x32_bf16 v[96:99], v[218:221], v[136:139], v[96:99]
	v_add_u32_e32 v218, v213, v169
	v_add_u32_e32 v213, v213, v168
	s_addc_u32 s47, s47, 0
	s_waitcnt lgkmcnt(0)
	v_mfma_f32_16x16x32_bf16 v[76:79], v[214:217], v[132:135], v[76:79]
	s_cmp_lg_u32 s46, 0x60000
	v_mfma_f32_16x16x32_bf16 v[80:83], v[214:217], v[136:139], v[80:83]
	ds_read_b64_tr_b16 v[214:215], v218 offset:17408
	ds_read_b64_tr_b16 v[216:217], v218 offset:22016
	s_waitcnt lgkmcnt(0)
	v_mfma_f32_16x16x32_bf16 v[100:103], v[214:217], v[132:135], v[100:103]
	v_mfma_f32_16x16x32_bf16 v[104:107], v[214:217], v[136:139], v[104:107]
	ds_read_b64_tr_b16 v[214:215], v222 offset:17536
	ds_read_b64_tr_b16 v[216:217], v222 offset:22144
	s_waitcnt lgkmcnt(0)
	v_mfma_f32_16x16x32_bf16 v[64:67], v[214:217], v[132:135], v[64:67]
	v_mfma_f32_16x16x32_bf16 v[68:71], v[214:217], v[136:139], v[68:71]
	ds_read_b64_tr_b16 v[214:215], v222 offset:17568
	ds_read_b64_tr_b16 v[216:217], v222 offset:22176
	s_waitcnt lgkmcnt(0)
	v_mfma_f32_16x16x32_bf16 v[56:59], v[214:217], v[132:135], v[56:59]
	v_mfma_f32_16x16x32_bf16 v[60:63], v[214:217], v[136:139], v[60:63]
	ds_read_b64_tr_b16 v[214:215], v222 offset:17600
	ds_read_b64_tr_b16 v[216:217], v222 offset:22208
	s_waitcnt lgkmcnt(0)
	v_mfma_f32_16x16x32_bf16 v[48:51], v[214:217], v[132:135], v[48:51]
	v_mfma_f32_16x16x32_bf16 v[52:55], v[214:217], v[136:139], v[52:55]
	ds_read_b64_tr_b16 v[214:215], v213 offset:17408
	ds_read_b64_tr_b16 v[216:217], v213 offset:22016
	v_mfma_f32_16x16x32_bf16 v[108:111], v[140:143], v[132:135], v[108:111]
	v_mfma_f32_16x16x32_bf16 v[112:115], v[140:143], v[136:139], v[112:115]
	s_waitcnt lgkmcnt(0)
	v_mfma_f32_16x16x32_bf16 v[40:43], v[214:217], v[132:135], v[40:43]
	v_cvt_pk_bf16_f32 v132, v181, v182
	v_cvt_pk_bf16_f32 v133, v183, v200
	v_cvt_pk_bf16_f32 v134, v201, v202
	v_mfma_f32_16x16x32_bf16 v[44:47], v[214:217], v[136:139], v[44:47]
	v_cvt_pk_bf16_f32 v135, v203, v204
	v_cvt_pk_bf16_f32 v136, v205, v206
	v_cvt_pk_bf16_f32 v137, v207, v208
	v_cvt_pk_bf16_f32 v138, v209, v210
	v_cvt_pk_bf16_f32 v139, v211, v212
	v_mfma_f32_16x16x32_bf16 v[108:111], v[140:143], v[132:135], v[108:111]
	v_add_u32_e32 v181, s4, v173
	v_mfma_f32_16x16x32_bf16 v[112:115], v[140:143], v[136:139], v[112:115]
	ds_read_b64_tr_b16 v[140:141], v222 offset:26624
	ds_read_b64_tr_b16 v[142:143], v222 offset:31232
	s_waitcnt lgkmcnt(0)
	v_mfma_f32_16x16x32_bf16 v[84:87], v[140:143], v[132:135], v[84:87]
	v_mfma_f32_16x16x32_bf16 v[88:91], v[140:143], v[136:139], v[88:91]
	ds_read_b64_tr_b16 v[140:141], v222 offset:26656
	ds_read_b64_tr_b16 v[142:143], v222 offset:31264
	s_waitcnt lgkmcnt(0)
	v_mfma_f32_16x16x32_bf16 v[92:95], v[140:143], v[132:135], v[92:95]
	v_mfma_f32_16x16x32_bf16 v[96:99], v[140:143], v[136:139], v[96:99]
	ds_read_b64_tr_b16 v[140:141], v222 offset:26688
	ds_read_b64_tr_b16 v[142:143], v222 offset:31296
	s_waitcnt lgkmcnt(0)
	v_mfma_f32_16x16x32_bf16 v[76:79], v[140:143], v[132:135], v[76:79]
	v_mfma_f32_16x16x32_bf16 v[80:83], v[140:143], v[136:139], v[80:83]
	ds_read_b64_tr_b16 v[140:141], v218 offset:26624
	ds_read_b64_tr_b16 v[142:143], v218 offset:31232
	s_waitcnt lgkmcnt(0)
	v_mfma_f32_16x16x32_bf16 v[100:103], v[140:143], v[132:135], v[100:103]
	v_mfma_f32_16x16x32_bf16 v[104:107], v[140:143], v[136:139], v[104:107]
	ds_read_b64_tr_b16 v[140:141], v222 offset:26752
	ds_read_b64_tr_b16 v[142:143], v222 offset:31360
	s_waitcnt lgkmcnt(0)
	v_mfma_f32_16x16x32_bf16 v[64:67], v[140:143], v[132:135], v[64:67]
	v_mfma_f32_16x16x32_bf16 v[68:71], v[140:143], v[136:139], v[68:71]
	ds_read_b64_tr_b16 v[140:141], v222 offset:26784
	ds_read_b64_tr_b16 v[142:143], v222 offset:31392
	s_waitcnt lgkmcnt(0)
	v_mfma_f32_16x16x32_bf16 v[56:59], v[140:143], v[132:135], v[56:59]
	v_mfma_f32_16x16x32_bf16 v[60:63], v[140:143], v[136:139], v[60:63]
	ds_read_b64_tr_b16 v[140:141], v222 offset:26816
	ds_read_b64_tr_b16 v[142:143], v222 offset:31424
	s_waitcnt lgkmcnt(0)
	v_mfma_f32_16x16x32_bf16 v[48:51], v[140:143], v[132:135], v[48:51]
	v_mfma_f32_16x16x32_bf16 v[52:55], v[140:143], v[136:139], v[52:55]
	ds_read_b64_tr_b16 v[140:141], v213 offset:26624
	ds_read_b64_tr_b16 v[142:143], v213 offset:31232
	s_waitcnt lgkmcnt(0)
	v_mfma_f32_16x16x32_bf16 v[40:43], v[140:143], v[132:135], v[40:43]
	s_waitcnt vmcnt(3)
	v_lshlrev_b32_e32 v132, 16, v131
	v_and_b32_e32 v133, 0xffff0000, v131
	v_pk_mul_f32 v[134:135], v[132:133], v[132:133]
	v_mfma_f32_16x16x32_bf16 v[44:47], v[140:143], v[136:139], v[44:47]
	v_lshlrev_b32_e32 v142, 16, v128
	v_and_b32_e32 v143, 0xffff0000, v128
	v_lshlrev_b32_e32 v138, 16, v129
	v_and_b32_e32 v139, 0xffff0000, v129
	v_pk_mul_f32 v[128:129], v[142:143], v[142:143]
	v_pk_mul_f32 v[140:141], v[138:139], v[138:139]
	v_add_f32_e32 v128, v128, v129
	v_lshlrev_b32_e32 v136, 16, v130
	v_and_b32_e32 v137, 0xffff0000, v130
	v_add_f32_e32 v128, v140, v128
	v_pk_mul_f32 v[130:131], v[136:137], v[136:137]
	v_add_f32_e32 v128, v141, v128
	v_add_f32_e32 v128, v130, v128
	v_add_f32_e32 v128, v131, v128
	v_add_f32_e32 v128, v134, v128
	v_add_f32_e32 v128, v135, v128
	ds_bpermute_b32 v129, v171, v128
	s_waitcnt lgkmcnt(0)
	v_add_f32_e32 v128, v128, v129
	ds_bpermute_b32 v129, v195, v128
	s_waitcnt lgkmcnt(0)
	v_add_f32_e32 v128, v128, v129
	ds_bpermute_b32 v129, v196, v128
	s_waitcnt lgkmcnt(0)
	v_add_f32_e32 v128, v128, v129
	ds_bpermute_b32 v129, v197, v128
	s_waitcnt lgkmcnt(0)
; __device__ __forceinline__ float frcp(float x) { return __builtin_amdgcn_rcpf(x); }
; #define BAR_LDS() do { asm volatile("s_waitcnt lgkmcnt(0)" ::: "memory"); __builtin_amdgcn_s_barrier(); asm volatile("" ::: "memory"); } while (0)
; #define MEM_LOAD(kt) do { _Pragma("unroll") for (int ii = 0; ii < 2; ++ii) { const int cid = tid + 512 * ii; \
;         ukr[ii] = *(const u32x4*)(kvm + (size_t)((kt) * 64 + (cid >> 4)) * 1024 + hm * 128 + (cid & 15) * 8); \
;         uvr[ii] = *(const u32x4*)(kvm + (size_t)((kt) * 64 + (cid >> 4)) * 1024 + 512 + hm * 128 + (cid & 15) * 8); } } while (0)
; __device__ __forceinline__ void mem_unit(const Args& a, int l, LAS unsigned char* lds, int b, int hm, int qb) {
;     ...
;     MEM_STORE(0);
;     BAR_LDS();
;     for (int kt = 0; kt < 4; ++kt) {
;         if (kt < 3) MEM_LOAD(kt + 1);
;         attn_tile<128, false, 0>(Ks + (kt & 1) * 35840, 272, Vs + (kt & 1) * 35840, 288, qf, o, ol, fr, fq, 0, 0, 0, -gm, -gm);
;         if (kt < 3) MEM_STORE((kt + 1) & 1);
;         BAR_LDS();
;     }
;     ...
; #pragma unroll
;     for (int qt = 0; qt < 2; ++qt) {
;         const float inv = frcp(ol[qt][0]);
;         const size_t row = rowbase + q0 + qt * 16 + fr;
; #pragma unroll
;         for (int dt = 0; dt < 8; ++dt) { const int d0 = dt * 16 + fq * 4;
;             const u32x2 z = *(const u32x2*)(proj + row * NCOL + CZ + 1024 + hm * 128 + d0);
	v_add_f32_e32 v128, v128, v129
	v_fmamk_f32 v128, v128, 0x3c000000, v186
	v_rsq_f32_e32 v134, v128
	s_nop 0
	v_pk_mul_f32 v[128:129], v[134:135], v[142:143] op_sel_hi:[0,1]
	v_pk_mul_f32 v[130:131], v[134:135], v[138:139] op_sel_hi:[0,1]
	v_pk_mul_f32 v[128:129], v[4:5], v[128:129]
	v_pk_mul_f32 v[130:131], v[6:7], v[130:131]
	v_cvt_pk_bf16_f32 v128, v128, v129
	v_cvt_pk_bf16_f32 v129, v130, v131
	v_pk_mul_f32 v[130:131], v[134:135], v[136:137] op_sel_hi:[0,1]
	v_pk_mul_f32 v[132:133], v[134:135], v[132:133] op_sel_hi:[0,1]
	v_pk_mul_f32 v[130:131], v[0:1], v[130:131]
	v_pk_mul_f32 v[132:133], v[2:3], v[132:133]
	v_cvt_pk_bf16_f32 v130, v130, v131
	v_cvt_pk_bf16_f32 v131, v132, v133
	v_add_u32_e32 v132, v181, v174
	s_waitcnt vmcnt(1)
	v_lshlrev_b32_e32 v134, 16, v120
	v_and_b32_e32 v135, 0xffff0000, v120
	ds_write_b128 v132, v[128:131]
	v_lshlrev_b32_e32 v130, 16, v121
	v_and_b32_e32 v131, 0xffff0000, v121
	v_pk_mul_f32 v[120:121], v[134:135], v[134:135]
	v_add_u32_e32 v128, v181, v175
	v_pk_mul_f32 v[132:133], v[130:131], v[130:131]
	v_add_f32_e32 v120, v120, v121
	ds_write_b128 v128, v[124:127] offset:17408
	v_lshlrev_b32_e32 v128, 16, v122
	v_and_b32_e32 v129, 0xffff0000, v122
	v_add_f32_e32 v120, v132, v120
	v_lshlrev_b32_e32 v124, 16, v123
	v_and_b32_e32 v125, 0xffff0000, v123
	v_pk_mul_f32 v[122:123], v[128:129], v[128:129]
	v_add_f32_e32 v120, v133, v120
	v_add_f32_e32 v120, v122, v120
	v_pk_mul_f32 v[126:127], v[124:125], v[124:125]
	v_add_f32_e32 v120, v123, v120
	v_add_f32_e32 v120, v126, v120
	v_add_f32_e32 v120, v127, v120
	ds_bpermute_b32 v121, v171, v120
	s_waitcnt lgkmcnt(0)
	v_add_f32_e32 v120, v120, v121
	ds_bpermute_b32 v121, v195, v120
	s_waitcnt lgkmcnt(0)
	v_add_f32_e32 v120, v120, v121
	ds_bpermute_b32 v121, v196, v120
	s_waitcnt lgkmcnt(0)
	v_add_f32_e32 v120, v120, v121
	ds_bpermute_b32 v121, v197, v120
	s_waitcnt lgkmcnt(0)
	v_add_f32_e32 v120, v120, v121
	v_fmamk_f32 v120, v120, 0x3c000000, v186
	v_rsq_f32_e32 v126, v120
	s_nop 0
	v_pk_mul_f32 v[120:121], v[126:127], v[134:135] op_sel_hi:[0,1]
	v_pk_mul_f32 v[122:123], v[126:127], v[130:131] op_sel_hi:[0,1]
	v_pk_mul_f32 v[120:121], v[4:5], v[120:121]
	v_pk_mul_f32 v[122:123], v[6:7], v[122:123]
	v_cvt_pk_bf16_f32 v120, v120, v121
	v_cvt_pk_bf16_f32 v121, v122, v123
	v_pk_mul_f32 v[122:123], v[126:127], v[128:129] op_sel_hi:[0,1]
	v_pk_mul_f32 v[124:125], v[126:127], v[124:125] op_sel_hi:[0,1]
	v_pk_mul_f32 v[122:123], v[0:1], v[122:123]
	v_pk_mul_f32 v[124:125], v[2:3], v[124:125]
	v_cvt_pk_bf16_f32 v122, v122, v123
	v_cvt_pk_bf16_f32 v123, v124, v125
	v_add_u32_e32 v124, v181, v177
	ds_write_b128 v124, v[120:123]
	v_add_u32_e32 v120, v181, v180
	s_waitcnt vmcnt(0)
	ds_write_b128 v120, v[116:119] offset:17408
	s_waitcnt lgkmcnt(0)
	s_barrier
	s_cbranch_scc1 .LBB0_520
	ds_read_b128 v[0:3], v176 offset:35840
	ds_read_b128 v[118:121], v176 offset:35904
	v_add_u32_e32 v141, v172, v170
	v_add_u32_e32 v116, 0x4400, v172
	s_lshl_b32 s6, s8, 1
	v_lshlrev_b32_e32 v144, 1, v144
	s_mov_b64 s[4:5], 0x1400
	v_lshl_add_u64 v[164:165], v[162:163], 0, s[6:7]
	v_lshl_add_u64 v[166:167], v[158:159], 0, s[6:7]
	v_lshl_add_u64 v[164:165], v[164:165], 0, v[144:145]
	v_lshl_add_u64 v[166:167], v[166:167], 0, v[144:145]
	v_lshl_add_u64 v[164:165], v[164:165], 0, s[4:5]
	v_lshl_add_u64 v[166:167], v[166:167], 0, s[4:5]
	global_load_dwordx2 v[200:201], v[164:165], off
	global_load_dwordx2 v[202:203], v[164:165], off offset:32
	global_load_dwordx2 v[204:205], v[164:165], off offset:64
	global_load_dwordx2 v[206:207], v[164:165], off offset:96
	global_load_dwordx2 v[208:209], v[164:165], off offset:128
	global_load_dwordx2 v[210:211], v[164:165], off offset:160
	global_load_dwordx2 v[212:213], v[164:165], off offset:192
	global_load_dwordx2 v[214:215], v[164:165], off offset:224
	global_load_dwordx2 v[216:217], v[166:167], off
	global_load_dwordx2 v[218:219], v[166:167], off offset:32
	global_load_dwordx2 v[220:221], v[166:167], off offset:64
	global_load_dwordx2 v[222:223], v[166:167], off offset:96
	global_load_dwordx2 v[224:225], v[166:167], off offset:128
	global_load_dwordx2 v[226:227], v[166:167], off offset:160
	global_load_dwordx2 v[228:229], v[166:167], off offset:192
	global_load_dwordx2 v[230:231], v[166:167], off offset:224
	v_lshlrev_b32_e32 v142, 1, v144
	v_mov_b32_e32 v143, 0
	s_add_i32 s14, s14, s3
	s_cmpk_gt_i32 s14, 0xff
	s_waitcnt lgkmcnt(1)
	v_mfma_f32_16x16x32_bf16 v[4:7], v[0:3], v[16:19], v[72:75]
	ds_read_b128 v[126:129], v176 offset:40256
	ds_read_b128 v[134:137], v176 offset:44608
	v_mfma_f32_16x16x32_bf16 v[0:3], v[0:3], v[24:27], v[72:75]
	s_waitcnt lgkmcnt(2)
	v_mfma_f32_16x16x32_bf16 v[4:7], v[118:121], v[20:23], v[4:7]
	v_mfma_f32_16x16x32_bf16 v[0:3], v[118:121], v[28:31], v[0:3]
	ds_read_b128 v[118:121], v176 offset:35968
	s_waitcnt lgkmcnt(0)
	v_mfma_f32_16x16x32_bf16 v[4:7], v[118:121], v[12:15], v[4:7]
	v_mfma_f32_16x16x32_bf16 v[0:3], v[118:121], v[36:39], v[0:3]
	ds_read_b128 v[118:121], v176 offset:36032
	s_waitcnt lgkmcnt(0)
	v_mfma_f32_16x16x32_bf16 v[4:7], v[118:121], v[8:11], v[4:7]
	s_nop 7
	v_exp_f32_e32 v4, v4
	v_mfma_f32_16x16x32_bf16 v[0:3], v[118:121], v[32:35], v[0:3]
	ds_read_b128 v[118:121], v176 offset:40192
	v_exp_f32_e32 v5, v5
	v_exp_f32_e32 v6, v6
	s_waitcnt lgkmcnt(0)
	v_mfma_f32_16x16x32_bf16 v[122:125], v[118:121], v[16:19], v[72:75]
	v_exp_f32_e32 v7, v7
	s_nop 1
	v_exp_f32_e32 v0, v0
	v_exp_f32_e32 v1, v1
	v_mfma_f32_16x16x32_bf16 v[118:121], v[118:121], v[24:27], v[72:75]
	v_exp_f32_e32 v2, v2
	v_exp_f32_e32 v3, v3
	v_mfma_f32_16x16x32_bf16 v[122:125], v[126:129], v[20:23], v[122:125]
	v_mfma_f32_16x16x32_bf16 v[118:121], v[126:129], v[28:31], v[118:121]
	ds_read_b128 v[126:129], v176 offset:40320
	s_waitcnt lgkmcnt(0)
; #define LAS __attribute__((address_space(3)))
; template <int D, int QT0>
; __device__ __forceinline__ void qk_tile(const LAS unsigned char* Ks, int KP, const bf16x8 (&qf)[2][D / 32], f32x4 (&s)[4][2], int fr, int fq, float b0, float b1) {
; #pragma unroll
;     for (int a = 0; a < 4; ++a) { s[a][0] = (f32x4){b0, b0, b0, b0}; s[a][1] = (f32x4){b1, b1, b1, b1}; }
; #pragma unroll
;     for (int a = 0; a < 4; ++a)
; #pragma unroll
;         for (int ks = 0; ks < D / 32; ++ks) { const bf16x8 kfr = *(const LAS bf16x8*)(Ks + (a * 16 + fr) * KP + (ks * 32 + fq * 8) * 2);
;             if (QT0 == 0) s[a][0] = MFMA16(kfr, qf[0][ks], s[a][0]);
;             s[a][1] = MFMA16(kfr, qf[1][ks], s[a][1]); }
; }
; template <int D, bool DIAG, int QT0>
; __device__ __forceinline__ void sm_pv_tile(f32x4 (&s)[4][2], const LAS unsigned char* Vs, int VP, f32x4 (&o)[D / 16][2], f32x4 (&ol)[2], int fr, int fq, int keyl0, int qla, int qlb) {
; #pragma unroll
;     for (int qt = QT0; qt < 2; ++qt) {
;         if (DIAG) {
;             const int ql = (qt == 0 ? qla : qlb) + fr - keyl0 - fq * 4;
; #pragma unroll
;             for (int a = 0; a < 4; ++a)
; #pragma unroll
;                 for (int jj = 0; jj < 4; ++jj) s[a][qt][jj] = (a * 16 + jj > ql) ? -1e30f : s[a][qt][jj];
;         }
; #pragma unroll
;         for (int a = 0; a < 4; ++a)
; #pragma unroll
;             for (int jj = 0; jj < 4; ++jj) s[a][qt][jj] = ex2(s[a][qt][jj]);
;     }
; #pragma unroll
;     for (int kst = 0; kst < 2; ++kst) {
;         bf16x8 pb[2];
; #pragma unroll
;         for (int qt = QT0; qt < 2; ++qt) { u32x4 pw; pw.x = pk2(s[2 * kst][qt][0], s[2 * kst][qt][1]); pw.y = pk2(s[2 * kst][qt][2], s[2 * kst][qt][3]);
;             pw.z = pk2(s[2 * kst + 1][qt][0], s[2 * kst + 1][qt][1]); pw.w = pk2(s[2 * kst + 1][qt][2], s[2 * kst + 1][qt][3]); pb[qt] = __builtin_bit_cast(bf16x8, pw); }
;         if (QT0 == 0) ol[0] = MFMA16(ONES8, pb[0], ol[0]);
;         ol[1] = MFMA16(ONES8, pb[1], ol[1]);
; #pragma unroll
;         for (int dt = 0; dt < D / 16; ++dt) { const s16x4 lo = tr4(Vs, VP, kst * 32 + fq * 4, dt * 16, fr), hi = tr4(Vs, VP, kst * 32 + 16 + fq * 4, dt * 16, fr);
;             const bf16x8 vf = __builtin_shufflevector(lo, hi, 0, 1, 2, 3, 4, 5, 6, 7);
;             if (QT0 == 0) o[dt][0] = MFMA16(vf, pb[0], o[dt][0]);
;             o[dt][1] = MFMA16(vf, pb[1], o[dt][1]); }
;     }
	v_mfma_f32_16x16x32_bf16 v[122:125], v[126:129], v[12:15], v[122:125]
	v_mfma_f32_16x16x32_bf16 v[118:121], v[126:129], v[36:39], v[118:121]
	ds_read_b128 v[126:129], v176 offset:40384
	s_waitcnt lgkmcnt(0)
	v_mfma_f32_16x16x32_bf16 v[122:125], v[126:129], v[8:11], v[122:125]
	v_mfma_f32_16x16x32_bf16 v[118:121], v[126:129], v[32:35], v[118:121]
	ds_read_b128 v[126:129], v176 offset:44544
	s_waitcnt lgkmcnt(0)
	v_mfma_f32_16x16x32_bf16 v[130:133], v[126:129], v[16:19], v[72:75]
	v_mfma_f32_16x16x32_bf16 v[126:129], v[126:129], v[24:27], v[72:75]
	v_mfma_f32_16x16x32_bf16 v[130:133], v[134:137], v[20:23], v[130:133]
	v_mfma_f32_16x16x32_bf16 v[126:129], v[134:137], v[28:31], v[126:129]
	ds_read_b128 v[134:137], v176 offset:44672
	s_waitcnt lgkmcnt(0)
	v_mfma_f32_16x16x32_bf16 v[130:133], v[134:137], v[12:15], v[130:133]
	v_mfma_f32_16x16x32_bf16 v[126:129], v[134:137], v[36:39], v[126:129]
	ds_read_b128 v[134:137], v176 offset:44736
	s_waitcnt lgkmcnt(0)
	v_mfma_f32_16x16x32_bf16 v[130:133], v[134:137], v[8:11], v[130:133]
	v_mfma_f32_16x16x32_bf16 v[126:129], v[134:137], v[32:35], v[126:129]
	ds_read_b128 v[134:137], v176 offset:48896
	s_waitcnt lgkmcnt(0)
	v_mfma_f32_16x16x32_bf16 v[16:19], v[134:137], v[16:19], v[72:75]
	s_nop 4
	v_exp_f32_e32 v117, v126
	v_mfma_f32_16x16x32_bf16 v[24:27], v[134:137], v[24:27], v[72:75]
	v_exp_f32_e32 v134, v127
	v_exp_f32_e32 v135, v128
	v_exp_f32_e32 v136, v129
	ds_read_b128 v[72:75], v176 offset:48960
	s_waitcnt lgkmcnt(0)
	v_mfma_f32_16x16x32_bf16 v[16:19], v[72:75], v[20:23], v[16:19]
	v_mfma_f32_16x16x32_bf16 v[20:23], v[72:75], v[28:31], v[24:27]
	s_nop 2
	ds_read_b128 v[24:27], v176 offset:49024
	s_waitcnt lgkmcnt(0)
	v_mfma_f32_16x16x32_bf16 v[12:15], v[24:27], v[12:15], v[16:19]
	v_mfma_f32_16x16x32_bf16 v[16:19], v[24:27], v[36:39], v[20:23]
	v_exp_f32_e32 v38, v132
	v_exp_f32_e32 v39, v133
	s_nop 0
	ds_read_b128 v[20:23], v176 offset:49088
	s_waitcnt lgkmcnt(0)
	v_mfma_f32_16x16x32_bf16 v[8:11], v[20:23], v[8:11], v[12:15]
	ds_read_b64_tr_b16 v[26:27], v141 offset:57856
	ds_read_b64_tr_b16 v[24:25], v141 offset:53248
	ds_read_b64_tr_b16 v[28:29], v141 offset:53280
	ds_read_b64_tr_b16 v[30:31], v141 offset:57888
	s_nop 3
	v_exp_f32_e32 v72, v8
	v_mfma_f32_16x16x32_bf16 v[12:15], v[20:23], v[32:35], v[16:19]
	v_exp_f32_e32 v73, v9
	v_exp_f32_e32 v74, v10
	v_exp_f32_e32 v75, v11
	v_exp_f32_e32 v16, v122
	v_exp_f32_e32 v17, v123
	v_exp_f32_e32 v18, v124
	v_exp_f32_e32 v19, v125
	v_exp_f32_e32 v8, v118
	v_exp_f32_e32 v9, v119
	v_exp_f32_e32 v10, v120
	v_exp_f32_e32 v11, v121
	v_exp_f32_e32 v137, v12
	v_exp_f32_e32 v138, v13
	v_exp_f32_e32 v139, v14
	v_exp_f32_e32 v140, v15
	v_cvt_pk_bf16_f32 v12, v4, v5
	v_cvt_pk_bf16_f32 v13, v6, v7
	v_cvt_pk_bf16_f32 v14, v16, v17
	v_cvt_pk_bf16_f32 v15, v18, v19
	v_cvt_pk_bf16_f32 v16, v0, v1
	v_cvt_pk_bf16_f32 v17, v2, v3
	v_cvt_pk_bf16_f32 v18, v8, v9
	v_cvt_pk_bf16_f32 v19, v10, v11
	s_waitcnt lgkmcnt(2)
	v_mfma_f32_16x16x32_bf16 v[20:23], v[24:27], v[12:15], v[84:87]
	v_mov_b64_e32 v[0:1], s[68:69]
	v_mov_b64_e32 v[2:3], s[70:71]
	v_exp_f32_e32 v32, v130
	v_mfma_f32_16x16x32_bf16 v[24:27], v[24:27], v[16:19], v[88:91]
	v_exp_f32_e32 v33, v131
	v_cvt_pk_bf16_f32 v72, v72, v73
	v_cvt_pk_bf16_f32 v73, v74, v75
	s_waitcnt lgkmcnt(0)
	v_mfma_f32_16x16x32_bf16 v[84:87], v[28:31], v[12:15], v[92:95]
	v_cvt_pk_bf16_f32 v74, v117, v134
	v_cvt_pk_bf16_f32 v75, v135, v136
	v_mfma_f32_16x16x32_bf16 v[88:91], v[28:31], v[16:19], v[96:99]
	ds_read_b64_tr_b16 v[28:29], v141 offset:53312
	ds_read_b64_tr_b16 v[30:31], v141 offset:57920
	s_waitcnt lgkmcnt(0)
	v_mfma_f32_16x16x32_bf16 v[96:99], v[28:31], v[16:19], v[80:83]
	s_nop 2
	v_add_u32_e32 v82, v172, v169
	v_add_u32_e32 v83, v172, v168
	v_mfma_f32_16x16x32_bf16 v[92:95], v[28:31], v[12:15], v[76:79]
	ds_read_b64_tr_b16 v[28:29], v82 offset:53248
	ds_read_b64_tr_b16 v[30:31], v82 offset:57856
	s_nop 0
	v_cvt_pk_bf16_f32 v76, v137, v138
	s_waitcnt lgkmcnt(0)
	v_mfma_f32_16x16x32_bf16 v[100:103], v[28:31], v[12:15], v[100:103]
	v_cvt_pk_bf16_f32 v77, v139, v140
	v_mfma_f32_16x16x32_bf16 v[104:107], v[28:31], v[16:19], v[104:107]
	ds_read_b64_tr_b16 v[28:29], v141 offset:53376
	ds_read_b64_tr_b16 v[30:31], v141 offset:57984
	v_mfma_f32_16x16x32_bf16 v[4:7], v[0:3], v[12:15], v[108:111]
	v_mfma_f32_16x16x32_bf16 v[8:11], v[0:3], v[16:19], v[112:115]
	s_waitcnt lgkmcnt(0)
	v_mfma_f32_16x16x32_bf16 v[108:111], v[28:31], v[12:15], v[64:67]
	v_mfma_f32_16x16x32_bf16 v[112:115], v[28:31], v[16:19], v[68:71]
	ds_read_b64_tr_b16 v[28:29], v141 offset:53408
	ds_read_b64_tr_b16 v[30:31], v141 offset:58016
	s_nop 0
	v_cvt_pk_bf16_f32 v70, v32, v33
	s_waitcnt lgkmcnt(0)
	v_mfma_f32_16x16x32_bf16 v[118:121], v[28:31], v[12:15], v[56:59]
	v_cvt_pk_bf16_f32 v71, v38, v39
	v_mfma_f32_16x16x32_bf16 v[122:125], v[28:31], v[16:19], v[60:63]
	ds_read_b64_tr_b16 v[28:29], v141 offset:53440
	ds_read_b64_tr_b16 v[30:31], v141 offset:58048
	s_waitcnt lgkmcnt(0)
	v_mfma_f32_16x16x32_bf16 v[126:129], v[28:31], v[12:15], v[48:51]
	v_mfma_f32_16x16x32_bf16 v[130:133], v[28:31], v[16:19], v[52:55]
	ds_read_b64_tr_b16 v[28:29], v83 offset:53248
	ds_read_b64_tr_b16 v[30:31], v83 offset:57856
	s_waitcnt lgkmcnt(0)
	v_mfma_f32_16x16x32_bf16 v[34:37], v[28:31], v[12:15], v[40:43]
	v_mfma_f32_16x16x32_bf16 v[66:69], v[28:31], v[16:19], v[44:47]
	v_mfma_f32_16x16x32_bf16 v[62:65], v[0:3], v[70:73], v[4:7]
	v_mfma_f32_16x16x32_bf16 v[28:31], v[0:3], v[74:77], v[8:11]
	ds_read_b64_tr_b16 v[0:1], v141 offset:62464
	s_nop 0
	v_add_u32_e32 v6, v116, v170
	ds_read_b64_tr_b16 v[2:3], v6 offset:49664
	ds_read_b64_tr_b16 v[4:5], v6 offset:49696
	s_waitcnt lgkmcnt(1)
; __device__ __forceinline__ unsigned pk2(float lo, float hi) { f32x2_t v = {lo, hi}; bf16x2_t b = __builtin_convertvector(v, bf16x2_t); return __builtin_bit_cast(unsigned, b); }
; __device__ __forceinline__ float bflo(unsigned u) { return __uint_as_float(u << 16); }
; __device__ __forceinline__ float bfhi(unsigned u) { return __uint_as_float(u & 0xffff0000u); }
; __device__ __forceinline__ float frcp(float x) { return __builtin_amdgcn_rcpf(x); }
; __device__ __forceinline__ float silu(float x) { return x * frcp(1.f + fexp(-x)); }
; __device__ __forceinline__ void mem_unit(const Args& a, int l, LAS unsigned char* lds, int b, int hm, int qb) {
;     ...
; #pragma unroll
;     for (int qt = 0; qt < 2; ++qt) {
;         const float inv = frcp(ol[qt][0]);
;         const size_t row = rowbase + q0 + qt * 16 + fr;
; #pragma unroll
;         for (int dt = 0; dt < 8; ++dt) { const int d0 = dt * 16 + fq * 4;
;             const u32x2 z = *(const u32x2*)(proj + row * NCOL + CZ + 1024 + hm * 128 + d0);
;             u32x2 y; y.x = pk2(o[dt][qt][0] * inv * silu(bflo(z.x)), o[dt][qt][1] * inv * silu(bfhi(z.x))); y.y = pk2(o[dt][qt][2] * inv * silu(bflo(z.y)), o[dt][qt][3] * inv * silu(bfhi(z.y)));
;             *(u32x2*)(proj + row * NCOL + CQM + hm * 128 + d0) = y; }
	v_mfma_f32_16x16x32_bf16 v[78:81], v[0:3], v[70:73], v[20:23]
	v_lshl_add_u64 v[64:65], v[162:163], 0, s[6:7]
	v_lshl_add_u64 v[64:65], v[64:65], 0, v[144:145]
	v_rcp_f32_e32 v62, v62
	v_mfma_f32_16x16x32_bf16 v[30:33], v[0:3], v[74:77], v[24:27]
	ds_read_b64_tr_b16 v[2:3], v141 offset:62496
	s_waitcnt lgkmcnt(0)
	v_mfma_f32_16x16x32_bf16 v[58:61], v[2:5], v[70:73], v[84:87]
	s_nop 7
	v_pk_mul_f32 v[58:59], v[62:63], v[58:59] op_sel_hi:[0,1]
	v_mfma_f32_16x16x32_bf16 v[24:27], v[2:5], v[74:77], v[88:91]
	ds_read_b64_tr_b16 v[0:1], v141 offset:62528
	ds_read_b64_tr_b16 v[2:3], v6 offset:49728
	v_pk_mul_f32 v[60:61], v[62:63], v[60:61] op_sel_hi:[0,1]
	s_waitcnt lgkmcnt(0)
	v_mfma_f32_16x16x32_bf16 v[54:57], v[0:3], v[70:73], v[92:95]
	v_mfma_f32_16x16x32_bf16 v[20:23], v[0:3], v[74:77], v[96:99]
	v_add_u32_e32 v2, v116, v169
	ds_read_b64_tr_b16 v[0:1], v82 offset:62464
	ds_read_b64_tr_b16 v[2:3], v2 offset:49664
	s_waitcnt lgkmcnt(0)
	v_mfma_f32_16x16x32_bf16 v[50:53], v[0:3], v[70:73], v[100:103]
	s_nop 1
	v_mul_f32_e64 v54, v62, v54
	v_mul_f32_e64 v55, v62, v55
	v_pk_mul_f32 v[56:57], v[62:63], v[56:57] op_sel_hi:[0,1]
	s_nop 2
	v_pk_mul_f32 v[50:51], v[62:63], v[50:51] op_sel_hi:[0,1]
	v_mfma_f32_16x16x32_bf16 v[16:19], v[0:3], v[74:77], v[104:107]
	ds_read_b64_tr_b16 v[0:1], v141 offset:62592
	ds_read_b64_tr_b16 v[2:3], v6 offset:49792
	v_pk_mul_f32 v[52:53], v[62:63], v[52:53] op_sel_hi:[0,1]
	s_waitcnt lgkmcnt(0)
	v_mfma_f32_16x16x32_bf16 v[46:49], v[0:3], v[70:73], v[108:111]
	v_mfma_f32_16x16x32_bf16 v[12:15], v[0:3], v[74:77], v[112:115]
	ds_read_b64_tr_b16 v[0:1], v141 offset:62624
	ds_read_b64_tr_b16 v[2:3], v6 offset:49824
	s_nop 4
	v_pk_mul_f32 v[46:47], v[62:63], v[46:47] op_sel_hi:[0,1]
	v_pk_mul_f32 v[48:49], v[62:63], v[48:49] op_sel_hi:[0,1]
	s_waitcnt lgkmcnt(0)
	v_mfma_f32_16x16x32_bf16 v[42:45], v[0:3], v[70:73], v[118:121]
	v_mfma_f32_16x16x32_bf16 v[8:11], v[0:3], v[74:77], v[122:125]
	ds_read_b64_tr_b16 v[0:1], v141 offset:62656
	ds_read_b64_tr_b16 v[2:3], v6 offset:49856
	s_nop 4
	v_pk_mul_f32 v[42:43], v[62:63], v[42:43] op_sel_hi:[0,1]
	v_pk_mul_f32 v[44:45], v[62:63], v[44:45] op_sel_hi:[0,1]
	s_waitcnt lgkmcnt(0)
	v_mfma_f32_16x16x32_bf16 v[38:41], v[0:3], v[70:73], v[126:129]
	v_mfma_f32_16x16x32_bf16 v[4:7], v[0:3], v[74:77], v[130:133]
	v_add_u32_e32 v2, v116, v168
	ds_read_b64_tr_b16 v[0:1], v83 offset:62464
	ds_read_b64_tr_b16 v[2:3], v2 offset:49664
	s_waitcnt lgkmcnt(0)
	v_mfma_f32_16x16x32_bf16 v[34:37], v[0:3], v[70:73], v[34:37]
	s_waitcnt lgkmcnt(0)
	s_barrier
	v_mfma_f32_16x16x32_bf16 v[0:3], v[0:3], v[74:77], v[66:69]
	v_mul_f32_e64 v72, v62, v78
	v_mul_f32_e64 v73, v62, v79
	v_pk_mul_f32 v[38:39], v[62:63], v[38:39] op_sel_hi:[0,1]
	v_pk_mul_f32 v[40:41], v[62:63], v[40:41] op_sel_hi:[0,1]
	v_lshl_add_u64 v[66:67], v[64:65], 0, s[4:5]
	v_add_co_u32_e32 v64, vcc, s26, v64
	v_pk_mul_f32 v[34:35], v[62:63], v[34:35] op_sel_hi:[0,1]
	s_nop 0
	v_addc_co_u32_e32 v65, vcc, 0, v65, vcc
	s_waitcnt vmcnt(0)
	v_mov_b64_e32 v[64:65], v[200:201]
	v_pk_mul_f32 v[36:37], v[62:63], v[36:37] op_sel_hi:[0,1]
	s_waitcnt vmcnt(0)
	v_lshlrev_b32_e32 v68, 16, v64
	v_mul_f32_e32 v29, 0xbfb8aa3b, v68
	v_exp_f32_e32 v29, v29
	v_and_b32_e32 v69, 0xffff0000, v64
	v_lshlrev_b32_e32 v64, 16, v65
	v_and_b32_e32 v65, 0xffff0000, v65
	v_add_f32_e32 v29, 1.0, v29
	v_rcp_f32_e32 v70, v29
	v_mul_f32_e32 v29, 0xbfb8aa3b, v69
	v_exp_f32_e32 v29, v29
	s_nop 0
	v_add_f32_e32 v29, 1.0, v29
	v_rcp_f32_e32 v71, v29
	v_mul_f32_e32 v29, 0xbfb8aa3b, v64
	v_exp_f32_e32 v29, v29
	v_pk_mul_f32 v[68:69], v[70:71], v[68:69]
	s_nop 0
	v_pk_mul_f32 v[68:69], v[72:73], v[68:69]
	v_add_f32_e32 v29, 1.0, v29
	v_rcp_f32_e32 v70, v29
	v_mul_f32_e32 v29, 0xbfb8aa3b, v65
	v_exp_f32_e32 v29, v29
	v_pk_mul_f32 v[72:73], v[62:63], v[80:81] op_sel_hi:[0,1]
	v_cvt_pk_bf16_f32 v68, v68, v69
	v_add_f32_e32 v29, 1.0, v29
	v_rcp_f32_e32 v71, v29
	s_nop 0
	v_pk_mul_f32 v[64:65], v[70:71], v[64:65]
	s_nop 0
	v_pk_mul_f32 v[64:65], v[72:73], v[64:65]
	s_nop 0
	v_cvt_pk_bf16_f32 v69, v64, v65
	v_lshl_add_u64 v[64:65], v[160:161], 0, v[142:143]
	v_mov_b64_e32 v[232:233], v[68:69]
	v_mov_b64_e32 v[68:69], v[202:203]
	v_lshlrev_b32_e32 v70, 16, v68
	v_mul_f32_e32 v29, 0xbfb8aa3b, v70
	v_exp_f32_e32 v29, v29
	v_and_b32_e32 v71, 0xffff0000, v68
	v_lshlrev_b32_e32 v68, 16, v69
	v_and_b32_e32 v69, 0xffff0000, v69
	v_add_f32_e32 v29, 1.0, v29
	v_rcp_f32_e32 v72, v29
	v_mul_f32_e32 v29, 0xbfb8aa3b, v71
	v_exp_f32_e32 v29, v29
	s_nop 0
	v_add_f32_e32 v29, 1.0, v29
	v_rcp_f32_e32 v73, v29
	v_mul_f32_e32 v29, 0xbfb8aa3b, v68
	v_exp_f32_e32 v29, v29
	v_pk_mul_f32 v[70:71], v[72:73], v[70:71]
	s_nop 0
	v_pk_mul_f32 v[58:59], v[58:59], v[70:71]
	v_add_f32_e32 v29, 1.0, v29
	v_rcp_f32_e32 v70, v29
	v_mul_f32_e32 v29, 0xbfb8aa3b, v69
	v_exp_f32_e32 v29, v29
	v_cvt_pk_bf16_f32 v58, v58, v59
	v_add_f32_e32 v29, 1.0, v29
	v_rcp_f32_e32 v71, v29
	s_nop 0
	v_pk_mul_f32 v[68:69], v[70:71], v[68:69]
	s_nop 0
	v_pk_mul_f32 v[60:61], v[60:61], v[68:69]
	s_nop 0
	v_cvt_pk_bf16_f32 v59, v60, v61
	v_mov_b64_e32 v[234:235], v[58:59]
	global_store_dwordx4 v[64:65], v[232:235], off offset:2048
	v_mov_b64_e32 v[58:59], v[204:205]
	v_lshlrev_b32_e32 v60, 16, v58
	v_mul_f32_e32 v29, 0xbfb8aa3b, v60
	v_exp_f32_e32 v29, v29
	v_and_b32_e32 v61, 0xffff0000, v58
	v_lshlrev_b32_e32 v58, 16, v59
	v_and_b32_e32 v59, 0xffff0000, v59
	v_add_f32_e32 v29, 1.0, v29
	v_rcp_f32_e32 v68, v29
	v_mul_f32_e32 v29, 0xbfb8aa3b, v61
	v_exp_f32_e32 v29, v29
	s_nop 0
	v_add_f32_e32 v29, 1.0, v29
	v_rcp_f32_e32 v69, v29
	v_mul_f32_e32 v29, 0xbfb8aa3b, v58
	v_exp_f32_e32 v29, v29
	v_pk_mul_f32 v[60:61], v[68:69], v[60:61]
; __device__ __forceinline__ unsigned pk2(float lo, float hi) { f32x2_t v = {lo, hi}; bf16x2_t b = __builtin_convertvector(v, bf16x2_t); return __builtin_bit_cast(unsigned, b); }
; __device__ __forceinline__ float bflo(unsigned u) { return __uint_as_float(u << 16); }
; __device__ __forceinline__ float bfhi(unsigned u) { return __uint_as_float(u & 0xffff0000u); }
; __device__ __forceinline__ float frcp(float x) { return __builtin_amdgcn_rcpf(x); }
; __device__ __forceinline__ float silu(float x) { return x * frcp(1.f + fexp(-x)); }
; __device__ __forceinline__ void mem_unit(const Args& a, int l, LAS unsigned char* lds, int b, int hm, int qb) {
;     ...
; #pragma unroll
;     for (int qt = 0; qt < 2; ++qt) {
;         const float inv = frcp(ol[qt][0]);
;         const size_t row = rowbase + q0 + qt * 16 + fr;
; #pragma unroll
;         for (int dt = 0; dt < 8; ++dt) { const int d0 = dt * 16 + fq * 4;
;             const u32x2 z = *(const u32x2*)(proj + row * NCOL + CZ + 1024 + hm * 128 + d0);
;             u32x2 y; y.x = pk2(o[dt][qt][0] * inv * silu(bflo(z.x)), o[dt][qt][1] * inv * silu(bfhi(z.x))); y.y = pk2(o[dt][qt][2] * inv * silu(bflo(z.y)), o[dt][qt][3] * inv * silu(bfhi(z.y)));
;             *(u32x2*)(proj + row * NCOL + CQM + hm * 128 + d0) = y; }
	s_nop 0
	v_pk_mul_f32 v[54:55], v[54:55], v[60:61]
	v_add_f32_e32 v29, 1.0, v29
	v_rcp_f32_e32 v60, v29
	v_mul_f32_e32 v29, 0xbfb8aa3b, v59
	v_exp_f32_e32 v29, v29
	v_cvt_pk_bf16_f32 v54, v54, v55
	v_add_f32_e32 v29, 1.0, v29
	v_rcp_f32_e32 v61, v29
	s_nop 0
	v_pk_mul_f32 v[58:59], v[60:61], v[58:59]
	s_nop 0
	v_pk_mul_f32 v[56:57], v[56:57], v[58:59]
	s_nop 0
	v_cvt_pk_bf16_f32 v55, v56, v57
	v_mov_b64_e32 v[236:237], v[54:55]
	v_mov_b64_e32 v[54:55], v[206:207]
	v_lshlrev_b32_e32 v56, 16, v54
	v_mul_f32_e32 v29, 0xbfb8aa3b, v56
	v_exp_f32_e32 v29, v29
	v_and_b32_e32 v57, 0xffff0000, v54
	v_lshlrev_b32_e32 v54, 16, v55
	v_and_b32_e32 v55, 0xffff0000, v55
	v_add_f32_e32 v29, 1.0, v29
	v_rcp_f32_e32 v58, v29
	v_mul_f32_e32 v29, 0xbfb8aa3b, v57
	v_exp_f32_e32 v29, v29
	s_nop 0
	v_add_f32_e32 v29, 1.0, v29
	v_rcp_f32_e32 v59, v29
	v_mul_f32_e32 v29, 0xbfb8aa3b, v54
	v_exp_f32_e32 v29, v29
	v_pk_mul_f32 v[56:57], v[58:59], v[56:57]
	s_nop 0
	v_pk_mul_f32 v[50:51], v[50:51], v[56:57]
	v_add_f32_e32 v29, 1.0, v29
	v_rcp_f32_e32 v56, v29
	v_mul_f32_e32 v29, 0xbfb8aa3b, v55
	v_exp_f32_e32 v29, v29
	v_cvt_pk_bf16_f32 v50, v50, v51
	v_add_f32_e32 v29, 1.0, v29
	v_rcp_f32_e32 v57, v29
	s_nop 0
	v_pk_mul_f32 v[54:55], v[56:57], v[54:55]
	s_nop 0
	v_pk_mul_f32 v[52:53], v[52:53], v[54:55]
	s_nop 0
	v_cvt_pk_bf16_f32 v51, v52, v53
	v_mov_b64_e32 v[238:239], v[50:51]
	global_store_dwordx4 v[64:65], v[236:239], off offset:2112
	v_mov_b64_e32 v[50:51], v[208:209]
	v_lshlrev_b32_e32 v52, 16, v50
	v_mul_f32_e32 v29, 0xbfb8aa3b, v52
	v_exp_f32_e32 v29, v29
	v_and_b32_e32 v53, 0xffff0000, v50
	v_lshlrev_b32_e32 v50, 16, v51
	v_and_b32_e32 v51, 0xffff0000, v51
	v_add_f32_e32 v29, 1.0, v29
	v_rcp_f32_e32 v54, v29
	v_mul_f32_e32 v29, 0xbfb8aa3b, v53
	v_exp_f32_e32 v29, v29
	s_nop 0
	v_add_f32_e32 v29, 1.0, v29
	v_rcp_f32_e32 v55, v29
	v_mul_f32_e32 v29, 0xbfb8aa3b, v50
	v_exp_f32_e32 v29, v29
	v_pk_mul_f32 v[52:53], v[54:55], v[52:53]
	s_nop 0
	v_pk_mul_f32 v[46:47], v[46:47], v[52:53]
	v_add_f32_e32 v29, 1.0, v29
	v_rcp_f32_e32 v52, v29
	v_mul_f32_e32 v29, 0xbfb8aa3b, v51
	v_exp_f32_e32 v29, v29
	v_cvt_pk_bf16_f32 v46, v46, v47
	v_add_f32_e32 v29, 1.0, v29
	v_rcp_f32_e32 v53, v29
	s_nop 0
	v_pk_mul_f32 v[50:51], v[52:53], v[50:51]
	s_nop 0
	v_pk_mul_f32 v[48:49], v[48:49], v[50:51]
	s_nop 0
	v_cvt_pk_bf16_f32 v47, v48, v49
	v_mov_b64_e32 v[240:241], v[46:47]
	v_mov_b64_e32 v[46:47], v[210:211]
	v_lshlrev_b32_e32 v48, 16, v46
	v_mul_f32_e32 v29, 0xbfb8aa3b, v48
	v_exp_f32_e32 v29, v29
	v_and_b32_e32 v49, 0xffff0000, v46
	v_lshlrev_b32_e32 v46, 16, v47
	v_and_b32_e32 v47, 0xffff0000, v47
	v_add_f32_e32 v29, 1.0, v29
	v_rcp_f32_e32 v50, v29
	v_mul_f32_e32 v29, 0xbfb8aa3b, v49
	v_exp_f32_e32 v29, v29
	s_nop 0
	v_add_f32_e32 v29, 1.0, v29
	v_rcp_f32_e32 v51, v29
	v_mul_f32_e32 v29, 0xbfb8aa3b, v46
	v_exp_f32_e32 v29, v29
	v_pk_mul_f32 v[48:49], v[50:51], v[48:49]
	s_nop 0
	v_pk_mul_f32 v[42:43], v[42:43], v[48:49]
	v_add_f32_e32 v29, 1.0, v29
	v_rcp_f32_e32 v48, v29
	v_mul_f32_e32 v29, 0xbfb8aa3b, v47
	v_exp_f32_e32 v29, v29
	v_cvt_pk_bf16_f32 v42, v42, v43
	v_add_f32_e32 v29, 1.0, v29
	v_rcp_f32_e32 v49, v29
	s_nop 0
	v_pk_mul_f32 v[46:47], v[48:49], v[46:47]
	s_nop 0
	v_pk_mul_f32 v[44:45], v[44:45], v[46:47]
	s_nop 0
	v_cvt_pk_bf16_f32 v43, v44, v45
	v_mov_b64_e32 v[242:243], v[42:43]
	global_store_dwordx4 v[64:65], v[240:243], off offset:2176
	v_mov_b64_e32 v[42:43], v[212:213]
	v_lshlrev_b32_e32 v44, 16, v42
	v_mul_f32_e32 v29, 0xbfb8aa3b, v44
	v_exp_f32_e32 v29, v29
	v_and_b32_e32 v45, 0xffff0000, v42
	v_lshlrev_b32_e32 v42, 16, v43
	v_and_b32_e32 v43, 0xffff0000, v43
	v_add_f32_e32 v29, 1.0, v29
	v_rcp_f32_e32 v46, v29
	v_mul_f32_e32 v29, 0xbfb8aa3b, v45
	v_exp_f32_e32 v29, v29
	s_nop 0
	v_add_f32_e32 v29, 1.0, v29
	v_rcp_f32_e32 v47, v29
	v_mul_f32_e32 v29, 0xbfb8aa3b, v42
	v_exp_f32_e32 v29, v29
	v_pk_mul_f32 v[44:45], v[46:47], v[44:45]
	s_nop 0
	v_pk_mul_f32 v[38:39], v[38:39], v[44:45]
	v_add_f32_e32 v29, 1.0, v29
	v_rcp_f32_e32 v44, v29
	v_mul_f32_e32 v29, 0xbfb8aa3b, v43
	v_exp_f32_e32 v29, v29
	v_cvt_pk_bf16_f32 v38, v38, v39
	v_add_f32_e32 v29, 1.0, v29
	v_rcp_f32_e32 v45, v29
	s_nop 0
	v_pk_mul_f32 v[42:43], v[44:45], v[42:43]
	s_nop 0
	v_pk_mul_f32 v[40:41], v[40:41], v[42:43]
	s_nop 0
	v_cvt_pk_bf16_f32 v39, v40, v41
	v_mov_b64_e32 v[180:181], v[38:39]
	v_mov_b64_e32 v[38:39], v[214:215]
	v_lshlrev_b32_e32 v40, 16, v38
	v_mul_f32_e32 v29, 0xbfb8aa3b, v40
	v_exp_f32_e32 v29, v29
	v_and_b32_e32 v41, 0xffff0000, v38
	v_lshlrev_b32_e32 v38, 16, v39
	v_and_b32_e32 v39, 0xffff0000, v39
	v_add_f32_e32 v29, 1.0, v29
	v_rcp_f32_e32 v42, v29
	v_mul_f32_e32 v29, 0xbfb8aa3b, v41
	v_exp_f32_e32 v29, v29
	s_nop 0
	v_add_f32_e32 v29, 1.0, v29
	v_rcp_f32_e32 v43, v29
	v_mul_f32_e32 v29, 0xbfb8aa3b, v38
	v_exp_f32_e32 v29, v29
	v_pk_mul_f32 v[40:41], v[42:43], v[40:41]
	s_nop 0
	v_pk_mul_f32 v[34:35], v[34:35], v[40:41]
	v_add_f32_e32 v29, 1.0, v29
	v_rcp_f32_e32 v40, v29
	v_mul_f32_e32 v29, 0xbfb8aa3b, v39
	v_exp_f32_e32 v29, v29
	v_cvt_pk_bf16_f32 v34, v34, v35
	v_add_f32_e32 v29, 1.0, v29
	v_rcp_f32_e32 v41, v29
	s_nop 0
	v_pk_mul_f32 v[38:39], v[40:41], v[38:39]
	s_nop 0
	v_pk_mul_f32 v[36:37], v[36:37], v[38:39]
	s_nop 0
	v_cvt_pk_bf16_f32 v35, v36, v37
	v_mov_b64_e32 v[182:183], v[34:35]
	global_store_dwordx4 v[64:65], v[180:183], off offset:2240
	v_rcp_f32_e32 v34, v28
	v_lshl_add_u64 v[28:29], v[158:159], 0, s[6:7]
	v_lshl_add_u64 v[28:29], v[28:29], 0, v[144:145]
	v_lshl_add_u64 v[36:37], v[28:29], 0, s[4:5]
	v_add_co_u32_e32 v28, vcc, s26, v28
	v_pk_mul_f32 v[30:31], v[34:35], v[30:31] op_sel_hi:[0,1]
	s_nop 0
	v_addc_co_u32_e32 v29, vcc, 0, v29, vcc
; __device__ __forceinline__ unsigned pk2(float lo, float hi) { f32x2_t v = {lo, hi}; bf16x2_t b = __builtin_convertvector(v, bf16x2_t); return __builtin_bit_cast(unsigned, b); }
; __device__ __forceinline__ float bflo(unsigned u) { return __uint_as_float(u << 16); }
; __device__ __forceinline__ float bfhi(unsigned u) { return __uint_as_float(u & 0xffff0000u); }
; __device__ __forceinline__ float frcp(float x) { return __builtin_amdgcn_rcpf(x); }
; __device__ __forceinline__ float silu(float x) { return x * frcp(1.f + fexp(-x)); }
; __device__ __forceinline__ void mem_unit(const Args& a, int l, LAS unsigned char* lds, int b, int hm, int qb) {
;     ...
; #pragma unroll
;     for (int qt = 0; qt < 2; ++qt) {
;         const float inv = frcp(ol[qt][0]);
;         const size_t row = rowbase + q0 + qt * 16 + fr;
; #pragma unroll
;         for (int dt = 0; dt < 8; ++dt) { const int d0 = dt * 16 + fq * 4;
;             const u32x2 z = *(const u32x2*)(proj + row * NCOL + CZ + 1024 + hm * 128 + d0);
;             u32x2 y; y.x = pk2(o[dt][qt][0] * inv * silu(bflo(z.x)), o[dt][qt][1] * inv * silu(bfhi(z.x))); y.y = pk2(o[dt][qt][2] * inv * silu(bflo(z.y)), o[dt][qt][3] * inv * silu(bfhi(z.y)));
;             *(u32x2*)(proj + row * NCOL + CQM + hm * 128 + d0) = y; }
;     }
	v_mov_b64_e32 v[28:29], v[216:217]
	v_pk_mul_f32 v[32:33], v[34:35], v[32:33] op_sel_hi:[0,1]
	v_pk_mul_f32 v[24:25], v[34:35], v[24:25] op_sel_hi:[0,1]
	v_pk_mul_f32 v[26:27], v[34:35], v[26:27] op_sel_hi:[0,1]
	v_pk_mul_f32 v[20:21], v[34:35], v[20:21] op_sel_hi:[0,1]
	v_pk_mul_f32 v[22:23], v[34:35], v[22:23] op_sel_hi:[0,1]
	v_pk_mul_f32 v[16:17], v[34:35], v[16:17] op_sel_hi:[0,1]
	v_pk_mul_f32 v[18:19], v[34:35], v[18:19] op_sel_hi:[0,1]
	v_pk_mul_f32 v[12:13], v[34:35], v[12:13] op_sel_hi:[0,1]
	v_pk_mul_f32 v[14:15], v[34:35], v[14:15] op_sel_hi:[0,1]
	v_pk_mul_f32 v[8:9], v[34:35], v[8:9] op_sel_hi:[0,1]
	v_pk_mul_f32 v[10:11], v[34:35], v[10:11] op_sel_hi:[0,1]
	v_pk_mul_f32 v[4:5], v[34:35], v[4:5] op_sel_hi:[0,1]
	v_pk_mul_f32 v[6:7], v[34:35], v[6:7] op_sel_hi:[0,1]
	v_pk_mul_f32 v[0:1], v[34:35], v[0:1] op_sel_hi:[0,1]
	v_pk_mul_f32 v[2:3], v[34:35], v[2:3] op_sel_hi:[0,1]
	v_lshlrev_b32_e32 v38, 16, v28
	v_and_b32_e32 v39, 0xffff0000, v28
	v_mul_f32_e32 v28, 0xbfb8aa3b, v38
	v_exp_f32_e32 v28, v28
	s_nop 0
	v_add_f32_e32 v28, 1.0, v28
	v_rcp_f32_e32 v40, v28
	v_mul_f32_e32 v28, 0xbfb8aa3b, v39
	v_exp_f32_e32 v28, v28
	s_nop 0
	v_add_f32_e32 v28, 1.0, v28
	v_rcp_f32_e32 v41, v28
	v_lshlrev_b32_e32 v28, 16, v29
	v_and_b32_e32 v29, 0xffff0000, v29
	v_pk_mul_f32 v[38:39], v[40:41], v[38:39]
	s_nop 0
	v_pk_mul_f32 v[30:31], v[30:31], v[38:39]
	s_nop 0
	v_cvt_pk_bf16_f32 v30, v30, v31
	v_mul_f32_e32 v31, 0xbfb8aa3b, v28
	v_exp_f32_e32 v31, v31
	s_nop 0
	v_add_f32_e32 v31, 1.0, v31
	v_rcp_f32_e32 v38, v31
	v_mul_f32_e32 v31, 0xbfb8aa3b, v29
	v_exp_f32_e32 v31, v31
	s_nop 0
	v_add_f32_e32 v31, 1.0, v31
	v_rcp_f32_e32 v39, v31
	s_nop 0
	v_pk_mul_f32 v[28:29], v[38:39], v[28:29]
	s_nop 0
	v_pk_mul_f32 v[28:29], v[32:33], v[28:29]
	s_nop 0
	v_cvt_pk_bf16_f32 v31, v28, v29
	v_lshl_add_u64 v[28:29], v[156:157], 0, v[142:143]
	v_mov_b64_e32 v[232:233], v[30:31]
	v_mov_b64_e32 v[30:31], v[218:219]
	v_lshlrev_b32_e32 v32, 16, v30
	v_and_b32_e32 v33, 0xffff0000, v30
	v_mul_f32_e32 v30, 0xbfb8aa3b, v32
	v_exp_f32_e32 v30, v30
	s_nop 0
	v_add_f32_e32 v30, 1.0, v30
	v_rcp_f32_e32 v38, v30
	v_mul_f32_e32 v30, 0xbfb8aa3b, v33
	v_exp_f32_e32 v30, v30
	s_nop 0
	v_add_f32_e32 v30, 1.0, v30
	v_rcp_f32_e32 v39, v30
	v_lshlrev_b32_e32 v30, 16, v31
	v_and_b32_e32 v31, 0xffff0000, v31
	v_pk_mul_f32 v[32:33], v[38:39], v[32:33]
	s_nop 0
	v_pk_mul_f32 v[24:25], v[24:25], v[32:33]
	s_nop 0
	v_cvt_pk_bf16_f32 v24, v24, v25
	v_mul_f32_e32 v25, 0xbfb8aa3b, v30
	v_exp_f32_e32 v25, v25
	s_nop 0
	v_add_f32_e32 v25, 1.0, v25
	v_rcp_f32_e32 v32, v25
	v_mul_f32_e32 v25, 0xbfb8aa3b, v31
	v_exp_f32_e32 v25, v25
	s_nop 0
	v_add_f32_e32 v25, 1.0, v25
	v_rcp_f32_e32 v33, v25
	s_nop 0
	v_pk_mul_f32 v[30:31], v[32:33], v[30:31]
	s_nop 0
	v_pk_mul_f32 v[26:27], v[26:27], v[30:31]
	s_nop 0
	v_cvt_pk_bf16_f32 v25, v26, v27
	v_mov_b64_e32 v[234:235], v[24:25]
	global_store_dwordx4 v[28:29], v[232:235], off offset:2048
	v_mov_b64_e32 v[24:25], v[220:221]
	v_lshlrev_b32_e32 v26, 16, v24
	v_and_b32_e32 v27, 0xffff0000, v24
	v_mul_f32_e32 v24, 0xbfb8aa3b, v26
	v_exp_f32_e32 v24, v24
	s_nop 0
	v_add_f32_e32 v24, 1.0, v24
	v_rcp_f32_e32 v30, v24
	v_mul_f32_e32 v24, 0xbfb8aa3b, v27
	v_exp_f32_e32 v24, v24
	s_nop 0
	v_add_f32_e32 v24, 1.0, v24
	v_rcp_f32_e32 v31, v24
	v_lshlrev_b32_e32 v24, 16, v25
	v_and_b32_e32 v25, 0xffff0000, v25
	v_pk_mul_f32 v[26:27], v[30:31], v[26:27]
	s_nop 0
	v_pk_mul_f32 v[20:21], v[20:21], v[26:27]
	s_nop 0
	v_cvt_pk_bf16_f32 v20, v20, v21
	v_mul_f32_e32 v21, 0xbfb8aa3b, v24
	v_exp_f32_e32 v21, v21
	s_nop 0
	v_add_f32_e32 v21, 1.0, v21
	v_rcp_f32_e32 v26, v21
	v_mul_f32_e32 v21, 0xbfb8aa3b, v25
	v_exp_f32_e32 v21, v21
	s_nop 0
	v_add_f32_e32 v21, 1.0, v21
	v_rcp_f32_e32 v27, v21
	s_nop 0
	v_pk_mul_f32 v[24:25], v[26:27], v[24:25]
	s_nop 0
	v_pk_mul_f32 v[22:23], v[22:23], v[24:25]
	s_nop 0
	v_cvt_pk_bf16_f32 v21, v22, v23
	v_mov_b64_e32 v[236:237], v[20:21]
	v_mov_b64_e32 v[20:21], v[222:223]
	v_lshlrev_b32_e32 v22, 16, v20
	v_and_b32_e32 v23, 0xffff0000, v20
	v_mul_f32_e32 v20, 0xbfb8aa3b, v22
	v_exp_f32_e32 v20, v20
	s_nop 0
	v_add_f32_e32 v20, 1.0, v20
	v_rcp_f32_e32 v24, v20
	v_mul_f32_e32 v20, 0xbfb8aa3b, v23
	v_exp_f32_e32 v20, v20
	s_nop 0
	v_add_f32_e32 v20, 1.0, v20
	v_rcp_f32_e32 v25, v20
	v_lshlrev_b32_e32 v20, 16, v21
	v_and_b32_e32 v21, 0xffff0000, v21
	v_pk_mul_f32 v[22:23], v[24:25], v[22:23]
	s_nop 0
	v_pk_mul_f32 v[16:17], v[16:17], v[22:23]
	s_nop 0
; __device__ __forceinline__ unsigned pk2(float lo, float hi) { f32x2_t v = {lo, hi}; bf16x2_t b = __builtin_convertvector(v, bf16x2_t); return __builtin_bit_cast(unsigned, b); }
; __device__ __forceinline__ float bflo(unsigned u) { return __uint_as_float(u << 16); }
; __device__ __forceinline__ float bfhi(unsigned u) { return __uint_as_float(u & 0xffff0000u); }
; __device__ __forceinline__ float frcp(float x) { return __builtin_amdgcn_rcpf(x); }
; __device__ __forceinline__ float silu(float x) { return x * frcp(1.f + fexp(-x)); }
; __device__ __forceinline__ void mem_unit(const Args& a, int l, LAS unsigned char* lds, int b, int hm, int qb) {
;     ...
; #pragma unroll
;     for (int qt = 0; qt < 2; ++qt) {
;         const float inv = frcp(ol[qt][0]);
;         const size_t row = rowbase + q0 + qt * 16 + fr;
; #pragma unroll
;         for (int dt = 0; dt < 8; ++dt) { const int d0 = dt * 16 + fq * 4;
;             const u32x2 z = *(const u32x2*)(proj + row * NCOL + CZ + 1024 + hm * 128 + d0);
;             u32x2 y; y.x = pk2(o[dt][qt][0] * inv * silu(bflo(z.x)), o[dt][qt][1] * inv * silu(bfhi(z.x))); y.y = pk2(o[dt][qt][2] * inv * silu(bflo(z.y)), o[dt][qt][3] * inv * silu(bfhi(z.y)));
;             *(u32x2*)(proj + row * NCOL + CQM + hm * 128 + d0) = y; }
;     }
	v_cvt_pk_bf16_f32 v16, v16, v17
	v_mul_f32_e32 v17, 0xbfb8aa3b, v20
	v_exp_f32_e32 v17, v17
	s_nop 0
	v_add_f32_e32 v17, 1.0, v17
	v_rcp_f32_e32 v22, v17
	v_mul_f32_e32 v17, 0xbfb8aa3b, v21
	v_exp_f32_e32 v17, v17
	s_nop 0
	v_add_f32_e32 v17, 1.0, v17
	v_rcp_f32_e32 v23, v17
	s_nop 0
	v_pk_mul_f32 v[20:21], v[22:23], v[20:21]
	s_nop 0
	v_pk_mul_f32 v[18:19], v[18:19], v[20:21]
	s_nop 0
	v_cvt_pk_bf16_f32 v17, v18, v19
	v_mov_b64_e32 v[238:239], v[16:17]
	global_store_dwordx4 v[28:29], v[236:239], off offset:2112
	v_mov_b64_e32 v[16:17], v[224:225]
	v_lshlrev_b32_e32 v18, 16, v16
	v_and_b32_e32 v19, 0xffff0000, v16
	v_mul_f32_e32 v16, 0xbfb8aa3b, v18
	v_exp_f32_e32 v16, v16
	s_nop 0
	v_add_f32_e32 v16, 1.0, v16
	v_rcp_f32_e32 v20, v16
	v_mul_f32_e32 v16, 0xbfb8aa3b, v19
	v_exp_f32_e32 v16, v16
	s_nop 0
	v_add_f32_e32 v16, 1.0, v16
	v_rcp_f32_e32 v21, v16
	v_lshlrev_b32_e32 v16, 16, v17
	v_and_b32_e32 v17, 0xffff0000, v17
	v_pk_mul_f32 v[18:19], v[20:21], v[18:19]
	s_nop 0
	v_pk_mul_f32 v[12:13], v[12:13], v[18:19]
	s_nop 0
	v_cvt_pk_bf16_f32 v12, v12, v13
	v_mul_f32_e32 v13, 0xbfb8aa3b, v16
	v_exp_f32_e32 v13, v13
	s_nop 0
	v_add_f32_e32 v13, 1.0, v13
	v_rcp_f32_e32 v18, v13
	v_mul_f32_e32 v13, 0xbfb8aa3b, v17
	v_exp_f32_e32 v13, v13
	s_nop 0
	v_add_f32_e32 v13, 1.0, v13
	v_rcp_f32_e32 v19, v13
	s_nop 0
	v_pk_mul_f32 v[16:17], v[18:19], v[16:17]
	s_nop 0
	v_pk_mul_f32 v[14:15], v[14:15], v[16:17]
	s_nop 0
	v_cvt_pk_bf16_f32 v13, v14, v15
	v_mov_b64_e32 v[240:241], v[12:13]
	v_mov_b64_e32 v[12:13], v[226:227]
	v_lshlrev_b32_e32 v14, 16, v12
	v_and_b32_e32 v15, 0xffff0000, v12
	v_mul_f32_e32 v12, 0xbfb8aa3b, v14
	v_exp_f32_e32 v12, v12
	s_nop 0
	v_add_f32_e32 v12, 1.0, v12
	v_rcp_f32_e32 v16, v12
	v_mul_f32_e32 v12, 0xbfb8aa3b, v15
	v_exp_f32_e32 v12, v12
	s_nop 0
	v_add_f32_e32 v12, 1.0, v12
	v_rcp_f32_e32 v17, v12
	v_lshlrev_b32_e32 v12, 16, v13
	v_and_b32_e32 v13, 0xffff0000, v13
	v_pk_mul_f32 v[14:15], v[16:17], v[14:15]
	s_nop 0
	v_pk_mul_f32 v[8:9], v[8:9], v[14:15]
	s_nop 0
	v_cvt_pk_bf16_f32 v8, v8, v9
	v_mul_f32_e32 v9, 0xbfb8aa3b, v12
	v_exp_f32_e32 v9, v9
	s_nop 0
	v_add_f32_e32 v9, 1.0, v9
	v_rcp_f32_e32 v14, v9
	v_mul_f32_e32 v9, 0xbfb8aa3b, v13
	v_exp_f32_e32 v9, v9
	s_nop 0
	v_add_f32_e32 v9, 1.0, v9
	v_rcp_f32_e32 v15, v9
	s_nop 0
	v_pk_mul_f32 v[12:13], v[14:15], v[12:13]
	s_nop 0
	v_pk_mul_f32 v[10:11], v[10:11], v[12:13]
	s_nop 0
	v_cvt_pk_bf16_f32 v9, v10, v11
	v_mov_b64_e32 v[242:243], v[8:9]
	global_store_dwordx4 v[28:29], v[240:243], off offset:2176
	v_mov_b64_e32 v[8:9], v[228:229]
	v_lshlrev_b32_e32 v10, 16, v8
	v_and_b32_e32 v11, 0xffff0000, v8
	v_mul_f32_e32 v8, 0xbfb8aa3b, v10
	v_exp_f32_e32 v8, v8
	s_nop 0
	v_add_f32_e32 v8, 1.0, v8
	v_rcp_f32_e32 v12, v8
	v_mul_f32_e32 v8, 0xbfb8aa3b, v11
	v_exp_f32_e32 v8, v8
	s_nop 0
	v_add_f32_e32 v8, 1.0, v8
	v_rcp_f32_e32 v13, v8
	v_lshlrev_b32_e32 v8, 16, v9
	v_and_b32_e32 v9, 0xffff0000, v9
	v_pk_mul_f32 v[10:11], v[12:13], v[10:11]
	s_nop 0
	v_pk_mul_f32 v[4:5], v[4:5], v[10:11]
	s_nop 0
	v_cvt_pk_bf16_f32 v4, v4, v5
	v_mul_f32_e32 v5, 0xbfb8aa3b, v8
	v_exp_f32_e32 v5, v5
	s_nop 0
	v_add_f32_e32 v5, 1.0, v5
	v_rcp_f32_e32 v10, v5
	v_mul_f32_e32 v5, 0xbfb8aa3b, v9
	v_exp_f32_e32 v5, v5
	s_nop 0
	v_add_f32_e32 v5, 1.0, v5
	v_rcp_f32_e32 v11, v5
	s_nop 0
	v_pk_mul_f32 v[8:9], v[10:11], v[8:9]
	s_nop 0
	v_pk_mul_f32 v[6:7], v[6:7], v[8:9]
	s_nop 0
	v_cvt_pk_bf16_f32 v5, v6, v7
	v_mov_b64_e32 v[180:181], v[4:5]
	v_mov_b64_e32 v[4:5], v[230:231]
	v_lshlrev_b32_e32 v6, 16, v4
	v_and_b32_e32 v7, 0xffff0000, v4
	v_mul_f32_e32 v4, 0xbfb8aa3b, v6
	v_exp_f32_e32 v4, v4
	s_nop 0
	v_add_f32_e32 v4, 1.0, v4
	v_rcp_f32_e32 v8, v4
	v_mul_f32_e32 v4, 0xbfb8aa3b, v7
	v_exp_f32_e32 v4, v4
	s_nop 0
	v_add_f32_e32 v4, 1.0, v4
	v_rcp_f32_e32 v9, v4
	v_lshlrev_b32_e32 v4, 16, v5
	v_and_b32_e32 v5, 0xffff0000, v5
	v_pk_mul_f32 v[6:7], v[8:9], v[6:7]
	s_nop 0
	v_pk_mul_f32 v[0:1], v[0:1], v[6:7]
	s_nop 0
	v_cvt_pk_bf16_f32 v0, v0, v1
	v_mul_f32_e32 v1, 0xbfb8aa3b, v4
	v_exp_f32_e32 v1, v1
	s_nop 0
	v_add_f32_e32 v1, 1.0, v1
	v_rcp_f32_e32 v6, v1
	v_mul_f32_e32 v1, 0xbfb8aa3b, v5
	v_exp_f32_e32 v1, v1
	s_nop 0
	v_add_f32_e32 v1, 1.0, v1
	v_rcp_f32_e32 v7, v1
	s_nop 0
	v_pk_mul_f32 v[4:5], v[6:7], v[4:5]
	s_nop 0
	v_pk_mul_f32 v[2:3], v[2:3], v[4:5]
	s_nop 0
	v_cvt_pk_bf16_f32 v1, v2, v3
	v_mov_b64_e32 v[182:183], v[0:1]
	global_store_dwordx4 v[28:29], v[180:183], off offset:2240
	s_cbranch_scc0 .LBB0_519

; __device__ __forceinline__ unsigned pk2(float lo, float hi) { f32x2_t v = {lo, hi}; bf16x2_t b = __builtin_convertvector(v, bf16x2_t); return __builtin_bit_cast(unsigned, b); }
; __device__ __forceinline__ float bflo(unsigned u) { return __uint_as_float(u << 16); }
; __device__ __forceinline__ float bfhi(unsigned u) { return __uint_as_float(u & 0xffff0000u); }
; __device__ __forceinline__ float frcp(float x) { return __builtin_amdgcn_rcpf(x); }
; __device__ __forceinline__ float silu(float x) { return x * frcp(1.f + fexp(-x)); }
; __device__ __forceinline__ void moba_unit(const Args& a, int l, LAS unsigned char* lds, int b, int h, int qb) {
;     ...
; #pragma unroll
;     for (int qt = 0; qt < 2; ++qt) {
;         const float inv = frcp(ol[qt][0]);
;         const size_t row = rowbase + qrow[qt] + fr;
; #pragma unroll
;         for (int dt = 0; dt < 4; ++dt) { const int d0 = dt * 16 + fq * 4;
;             const u32x2 z = zq[qt][dt];
;             u32x2 y; y.x = pk2(o[dt][qt][0] * inv * silu(bflo(z.x)), o[dt][qt][1] * inv * silu(bfhi(z.x))); y.y = pk2(o[dt][qt][2] * inv * silu(bflo(z.y)), o[dt][qt][3] * inv * silu(bfhi(z.y)));
;             *(u32x2*)(proj + row * NCOL + CQA + h * 64 + d0) = y; }
;     }
.LBB0_543:
	s_waitcnt vmcnt(7)
	v_lshlrev_b32_e32 v4, 16, v182
	v_mul_f32_e32 v1, 0xbfb8aa3b, v4
	v_exp_f32_e32 v1, v1
	v_rcp_f32_e32 v0, v8
	v_and_b32_e32 v5, 0xffff0000, v182
	v_lshl_add_u64 v[2:3], s[44:45], 0, v[142:143]
	v_add_f32_e32 v1, 1.0, v1
	v_rcp_f32_e32 v6, v1
	v_pk_mul_f32 v[8:9], v[92:93], v[0:1] op_sel_hi:[1,0]
	v_mul_f32_e32 v1, 0xbfb8aa3b, v5
	v_exp_f32_e32 v1, v1
	v_lshlrev_b32_e32 v144, 2, v170
	v_lshl_add_u64 v[2:3], v[2:3], 0, v[144:145]
	s_add_i32 s18, s18, s3
	v_add_f32_e32 v1, 1.0, v1
	v_rcp_f32_e32 v7, v1
	s_cmpk_gt_i32 s18, 0x1ff
	v_pk_mul_f32 v[4:5], v[6:7], v[4:5]
	v_lshlrev_b32_e32 v6, 16, v183
	v_mul_f32_e32 v1, 0xbfb8aa3b, v6
	v_exp_f32_e32 v1, v1
	v_and_b32_e32 v7, 0xffff0000, v183
	v_pk_mul_f32 v[4:5], v[4:5], v[8:9]
	v_add_f32_e32 v1, 1.0, v1
	v_rcp_f32_e32 v8, v1
	v_pk_mul_f32 v[10:11], v[94:95], v[0:1] op_sel_hi:[1,0]
	v_mul_f32_e32 v1, 0xbfb8aa3b, v7
	v_exp_f32_e32 v1, v1
	v_cvt_pk_bf16_f32 v4, v4, v5
	v_add_f32_e32 v1, 1.0, v1
	v_rcp_f32_e32 v9, v1
	s_nop 0
	v_pk_mul_f32 v[6:7], v[8:9], v[6:7]
	s_nop 0
	v_pk_mul_f32 v[6:7], v[6:7], v[10:11]
	s_nop 0
	v_cvt_pk_bf16_f32 v5, v6, v7
	v_mov_b32_e32 v12, v4
	v_mov_b32_e32 v13, v5
	s_waitcnt vmcnt(6)
	v_lshlrev_b32_e32 v4, 16, v174
	v_mul_f32_e32 v1, 0xbfb8aa3b, v4
	v_exp_f32_e32 v1, v1
	v_and_b32_e32 v5, 0xffff0000, v174
	v_add_f32_e32 v1, 1.0, v1
	v_rcp_f32_e32 v6, v1
	v_pk_mul_f32 v[8:9], v[88:89], v[0:1] op_sel_hi:[1,0]
	v_mul_f32_e32 v1, 0xbfb8aa3b, v5
	v_exp_f32_e32 v1, v1
	s_nop 0
	v_add_f32_e32 v1, 1.0, v1
	v_rcp_f32_e32 v7, v1
	s_nop 0
	v_pk_mul_f32 v[4:5], v[6:7], v[4:5]
	v_lshlrev_b32_e32 v6, 16, v175
	v_mul_f32_e32 v1, 0xbfb8aa3b, v6
	v_exp_f32_e32 v1, v1
	v_and_b32_e32 v7, 0xffff0000, v175
	v_pk_mul_f32 v[4:5], v[4:5], v[8:9]
	v_add_f32_e32 v1, 1.0, v1
	v_rcp_f32_e32 v8, v1
	v_pk_mul_f32 v[10:11], v[90:91], v[0:1] op_sel_hi:[1,0]
	v_mul_f32_e32 v1, 0xbfb8aa3b, v7
	v_exp_f32_e32 v1, v1
	v_cvt_pk_bf16_f32 v4, v4, v5
	v_add_f32_e32 v1, 1.0, v1
	v_rcp_f32_e32 v9, v1
	s_nop 0
	v_pk_mul_f32 v[6:7], v[8:9], v[6:7]
	s_nop 0
	v_pk_mul_f32 v[6:7], v[6:7], v[10:11]
	s_nop 0
	v_cvt_pk_bf16_f32 v5, v6, v7
	v_mov_b32_e32 v14, v4
	v_mov_b32_e32 v15, v5
	global_store_dwordx4 v[2:3], v[12:15], off
	s_waitcnt vmcnt(6)
	v_lshlrev_b32_e32 v4, 16, v172
	v_mul_f32_e32 v1, 0xbfb8aa3b, v4
	v_exp_f32_e32 v1, v1
	v_and_b32_e32 v5, 0xffff0000, v172
	v_add_f32_e32 v1, 1.0, v1
	v_rcp_f32_e32 v6, v1
	v_pk_mul_f32 v[8:9], v[100:101], v[0:1] op_sel_hi:[1,0]
	v_mul_f32_e32 v1, 0xbfb8aa3b, v5
	v_exp_f32_e32 v1, v1
	s_nop 0
	v_add_f32_e32 v1, 1.0, v1
	v_rcp_f32_e32 v7, v1
	s_nop 0
	v_pk_mul_f32 v[4:5], v[6:7], v[4:5]
	v_lshlrev_b32_e32 v6, 16, v173
	v_mul_f32_e32 v1, 0xbfb8aa3b, v6
	v_exp_f32_e32 v1, v1
	v_and_b32_e32 v7, 0xffff0000, v173
	v_pk_mul_f32 v[4:5], v[4:5], v[8:9]
	v_add_f32_e32 v1, 1.0, v1
	v_rcp_f32_e32 v8, v1
	v_pk_mul_f32 v[10:11], v[102:103], v[0:1] op_sel_hi:[1,0]
	v_mul_f32_e32 v1, 0xbfb8aa3b, v7
	v_exp_f32_e32 v1, v1
	v_cvt_pk_bf16_f32 v4, v4, v5
	v_add_f32_e32 v1, 1.0, v1
	v_rcp_f32_e32 v9, v1
	s_nop 0
	v_pk_mul_f32 v[6:7], v[8:9], v[6:7]
	s_nop 0
	v_pk_mul_f32 v[6:7], v[6:7], v[10:11]
	s_nop 0
	v_cvt_pk_bf16_f32 v5, v6, v7
	v_mov_b32_e32 v20, v4
	v_mov_b32_e32 v21, v5
	s_waitcnt vmcnt(5)
	v_lshlrev_b32_e32 v4, 16, v168
	v_mul_f32_e32 v1, 0xbfb8aa3b, v4
	v_exp_f32_e32 v1, v1
	v_and_b32_e32 v5, 0xffff0000, v168
	v_add_f32_e32 v1, 1.0, v1
	v_rcp_f32_e32 v6, v1
	v_pk_mul_f32 v[8:9], v[112:113], v[0:1] op_sel_hi:[1,0]
	v_mul_f32_e32 v1, 0xbfb8aa3b, v5
	v_exp_f32_e32 v1, v1
	s_nop 0
	v_add_f32_e32 v1, 1.0, v1
	v_rcp_f32_e32 v7, v1
	s_nop 0
	v_pk_mul_f32 v[4:5], v[6:7], v[4:5]
	s_nop 0
	v_pk_mul_f32 v[4:5], v[4:5], v[8:9]
	v_lshlrev_b32_e32 v6, 16, v169
	v_and_b32_e32 v7, 0xffff0000, v169
	v_cvt_pk_bf16_f32 v4, v4, v5
	v_mul_f32_e32 v1, 0xbfb8aa3b, v6
	v_mul_f32_e32 v5, 0xbfb8aa3b, v7
	v_exp_f32_e32 v1, v1
	v_exp_f32_e32 v5, v5
	v_add_f32_e32 v1, 1.0, v1
	v_add_f32_e32 v5, 1.0, v5
	v_rcp_f32_e32 v8, v1
	v_rcp_f32_e32 v9, v5
	v_pk_mul_f32 v[0:1], v[114:115], v[0:1] op_sel_hi:[1,0]
	v_pk_mul_f32 v[6:7], v[8:9], v[6:7]
	s_nop 0
	v_pk_mul_f32 v[0:1], v[6:7], v[0:1]
	s_nop 0
	v_cvt_pk_bf16_f32 v5, v0, v1
	v_mov_b32_e32 v22, v4
	v_mov_b32_e32 v23, v5
	global_store_dwordx4 v[2:3], v[20:23], off offset:64
	s_waitcnt vmcnt(5)
; __device__ __forceinline__ unsigned pk2(float lo, float hi) { f32x2_t v = {lo, hi}; bf16x2_t b = __builtin_convertvector(v, bf16x2_t); return __builtin_bit_cast(unsigned, b); }
; __device__ __forceinline__ float bflo(unsigned u) { return __uint_as_float(u << 16); }
; __device__ __forceinline__ float bfhi(unsigned u) { return __uint_as_float(u & 0xffff0000u); }
; __device__ __forceinline__ float frcp(float x) { return __builtin_amdgcn_rcpf(x); }
; __device__ __forceinline__ float silu(float x) { return x * frcp(1.f + fexp(-x)); }
; __device__ __forceinline__ void moba_unit(const Args& a, int l, LAS unsigned char* lds, int b, int h, int qb) {
;     ...
; #pragma unroll
;     for (int qt = 0; qt < 2; ++qt) {
;         const float inv = frcp(ol[qt][0]);
;         const size_t row = rowbase + qrow[qt] + fr;
; #pragma unroll
;         for (int dt = 0; dt < 4; ++dt) { const int d0 = dt * 16 + fq * 4;
;             const u32x2 z = zq[qt][dt];
;             u32x2 y; y.x = pk2(o[dt][qt][0] * inv * silu(bflo(z.x)), o[dt][qt][1] * inv * silu(bfhi(z.x))); y.y = pk2(o[dt][qt][2] * inv * silu(bflo(z.y)), o[dt][qt][3] * inv * silu(bfhi(z.y)));
;             *(u32x2*)(proj + row * NCOL + CQA + h * 64 + d0) = y; }
;     }
;     __syncthreads();
	v_lshlrev_b32_e32 v4, 16, v166
	v_mul_f32_e32 v1, 0xbfb8aa3b, v4
	v_exp_f32_e32 v1, v1
	v_rcp_f32_e32 v0, v96
	v_and_b32_e32 v5, 0xffff0000, v166
	v_lshl_add_u64 v[2:3], s[44:45], 0, v[140:141]
	v_add_f32_e32 v1, 1.0, v1
	v_rcp_f32_e32 v6, v1
	v_pk_mul_f32 v[8:9], v[104:105], v[0:1] op_sel_hi:[1,0]
	v_mul_f32_e32 v1, 0xbfb8aa3b, v5
	v_exp_f32_e32 v1, v1
	v_lshl_add_u64 v[2:3], v[2:3], 0, v[144:145]
	v_add_f32_e32 v1, 1.0, v1
	v_rcp_f32_e32 v7, v1
	s_nop 0
	v_pk_mul_f32 v[4:5], v[6:7], v[4:5]
	v_lshlrev_b32_e32 v6, 16, v167
	v_mul_f32_e32 v1, 0xbfb8aa3b, v6
	v_exp_f32_e32 v1, v1
	v_and_b32_e32 v7, 0xffff0000, v167
	v_pk_mul_f32 v[4:5], v[4:5], v[8:9]
	v_add_f32_e32 v1, 1.0, v1
	v_rcp_f32_e32 v8, v1
	v_pk_mul_f32 v[10:11], v[106:107], v[0:1] op_sel_hi:[1,0]
	v_mul_f32_e32 v1, 0xbfb8aa3b, v7
	v_exp_f32_e32 v1, v1
	v_cvt_pk_bf16_f32 v4, v4, v5
	v_add_f32_e32 v1, 1.0, v1
	v_rcp_f32_e32 v9, v1
	s_nop 0
	v_pk_mul_f32 v[6:7], v[8:9], v[6:7]
	s_nop 0
	v_pk_mul_f32 v[6:7], v[6:7], v[10:11]
	s_nop 0
	v_cvt_pk_bf16_f32 v5, v6, v7
	v_mov_b32_e32 v24, v4
	v_mov_b32_e32 v25, v5
	s_waitcnt vmcnt(4)
	v_lshlrev_b32_e32 v4, 16, v164
	v_mul_f32_e32 v1, 0xbfb8aa3b, v4
	v_exp_f32_e32 v1, v1
	v_and_b32_e32 v5, 0xffff0000, v164
	v_add_f32_e32 v1, 1.0, v1
	v_rcp_f32_e32 v6, v1
	v_pk_mul_f32 v[8:9], v[16:17], v[0:1] op_sel_hi:[1,0]
	v_mul_f32_e32 v1, 0xbfb8aa3b, v5
	v_exp_f32_e32 v1, v1
	s_nop 0
	v_add_f32_e32 v1, 1.0, v1
	v_rcp_f32_e32 v7, v1
	s_nop 0
	v_pk_mul_f32 v[4:5], v[6:7], v[4:5]
	v_lshlrev_b32_e32 v6, 16, v165
	v_mul_f32_e32 v1, 0xbfb8aa3b, v6
	v_exp_f32_e32 v1, v1
	v_and_b32_e32 v7, 0xffff0000, v165
	v_pk_mul_f32 v[4:5], v[4:5], v[8:9]
	v_add_f32_e32 v1, 1.0, v1
	v_rcp_f32_e32 v8, v1
	v_pk_mul_f32 v[10:11], v[18:19], v[0:1] op_sel_hi:[1,0]
	v_mul_f32_e32 v1, 0xbfb8aa3b, v7
	v_exp_f32_e32 v1, v1
	v_cvt_pk_bf16_f32 v4, v4, v5
	v_add_f32_e32 v1, 1.0, v1
	v_rcp_f32_e32 v9, v1
	s_nop 0
	v_pk_mul_f32 v[6:7], v[8:9], v[6:7]
	s_nop 0
	v_pk_mul_f32 v[6:7], v[6:7], v[10:11]
	s_nop 0
	v_cvt_pk_bf16_f32 v5, v6, v7
	v_mov_b32_e32 v26, v4
	v_mov_b32_e32 v27, v5
	global_store_dwordx4 v[2:3], v[24:27], off
	s_waitcnt vmcnt(4)
	v_lshlrev_b32_e32 v4, 16, v162
	v_mul_f32_e32 v1, 0xbfb8aa3b, v4
	v_exp_f32_e32 v1, v1
	v_and_b32_e32 v5, 0xffff0000, v162
	v_add_f32_e32 v1, 1.0, v1
	v_rcp_f32_e32 v6, v1
	v_pk_mul_f32 v[8:9], v[108:109], v[0:1] op_sel_hi:[1,0]
	v_mul_f32_e32 v1, 0xbfb8aa3b, v5
	v_exp_f32_e32 v1, v1
	s_nop 0
	v_add_f32_e32 v1, 1.0, v1
	v_rcp_f32_e32 v7, v1
	s_nop 0
	v_pk_mul_f32 v[4:5], v[6:7], v[4:5]
	v_lshlrev_b32_e32 v6, 16, v163
	v_mul_f32_e32 v1, 0xbfb8aa3b, v6
	v_exp_f32_e32 v1, v1
	v_and_b32_e32 v7, 0xffff0000, v163
	v_pk_mul_f32 v[4:5], v[4:5], v[8:9]
	v_add_f32_e32 v1, 1.0, v1
	v_rcp_f32_e32 v8, v1
	v_pk_mul_f32 v[10:11], v[110:111], v[0:1] op_sel_hi:[1,0]
	v_mul_f32_e32 v1, 0xbfb8aa3b, v7
	v_exp_f32_e32 v1, v1
	v_cvt_pk_bf16_f32 v4, v4, v5
	v_add_f32_e32 v1, 1.0, v1
	v_rcp_f32_e32 v9, v1
	s_nop 0
	v_pk_mul_f32 v[6:7], v[8:9], v[6:7]
	s_nop 0
	v_pk_mul_f32 v[6:7], v[6:7], v[10:11]
	s_nop 0
	v_cvt_pk_bf16_f32 v5, v6, v7
	v_mov_b32_e32 v28, v4
	v_mov_b32_e32 v29, v5
	s_waitcnt vmcnt(3)
	v_lshlrev_b32_e32 v4, 16, v160
	v_mul_f32_e32 v1, 0xbfb8aa3b, v4
	v_exp_f32_e32 v1, v1
	v_and_b32_e32 v5, 0xffff0000, v160
	v_add_f32_e32 v1, 1.0, v1
	v_rcp_f32_e32 v6, v1
	v_pk_mul_f32 v[8:9], v[132:133], v[0:1] op_sel_hi:[1,0]
	v_mul_f32_e32 v1, 0xbfb8aa3b, v5
	v_exp_f32_e32 v1, v1
	s_nop 0
	v_add_f32_e32 v1, 1.0, v1
	v_rcp_f32_e32 v7, v1
	s_nop 0
	v_pk_mul_f32 v[4:5], v[6:7], v[4:5]
	s_nop 0
	v_pk_mul_f32 v[4:5], v[4:5], v[8:9]
	v_lshlrev_b32_e32 v6, 16, v161
	v_and_b32_e32 v7, 0xffff0000, v161
	v_cvt_pk_bf16_f32 v4, v4, v5
	v_mul_f32_e32 v1, 0xbfb8aa3b, v6
	v_mul_f32_e32 v5, 0xbfb8aa3b, v7
	v_exp_f32_e32 v1, v1
	v_exp_f32_e32 v5, v5
	v_add_f32_e32 v1, 1.0, v1
	v_add_f32_e32 v5, 1.0, v5
	v_rcp_f32_e32 v8, v1
	v_rcp_f32_e32 v9, v5
	v_pk_mul_f32 v[0:1], v[134:135], v[0:1] op_sel_hi:[1,0]
	v_pk_mul_f32 v[6:7], v[8:9], v[6:7]
	s_nop 0
	v_pk_mul_f32 v[0:1], v[6:7], v[0:1]
	s_nop 0
	v_cvt_pk_bf16_f32 v5, v0, v1
	v_mov_b32_e32 v30, v4
	v_mov_b32_e32 v31, v5
	global_store_dwordx4 v[2:3], v[28:31], off offset:64
	s_waitcnt lgkmcnt(0)
	s_barrier
	s_cbranch_scc1 .LBB0_517

; #define LAS __attribute__((address_space(3)))
; __device__ __forceinline__ unsigned pk2(float lo, float hi) { f32x2_t v = {lo, hi}; bf16x2_t b = __builtin_convertvector(v, bf16x2_t); return __builtin_bit_cast(unsigned, b); }
; __device__ __forceinline__ float bflo(unsigned u) { return __uint_as_float(u << 16); }
; __device__ __forceinline__ float bfhi(unsigned u) { return __uint_as_float(u & 0xffff0000u); }
; __device__ __forceinline__ float frsq(float x) { return __builtin_amdgcn_rsqf(x); }
; __device__ __forceinline__ float silu(float x) { return x * frcp(1.f + fexp(-x)); }
; #define BAR_LDS() do { asm volatile("s_waitcnt lgkmcnt(0)" ::: "memory"); __builtin_amdgcn_s_barrier(); asm volatile("" ::: "memory"); } while (0)
; __device__ __forceinline__ void hgrn_stage3_unit(const Args& a, int l, LAS unsigned char* lds, int tid, int u, const HIn& in, HIn& nxt, int unext) {
;     ...
;     const float tot = SSQ[tt * 16 + fr] + SSQ[64 + tt * 16 + fr];
;     const float r = frsq(tot * (1.f / 128.f) + EPS);
; #pragma unroll
;     for (int v = 0; v < 4; ++v) { const int v0 = (vh * 4 + v) * 16 + fq * 4;
;         const f32x4 g = *(const LAS f32x4*)((const LAS float*)(lds + 106496 + 2048) + v0);
;         const u32x2 z = zz[v];
;         u32x2 y; y.x = pk2(o[v][0] * r * g.x * silu(bflo(z.x)), o[v][1] * r * g.y * silu(bfhi(z.x))); y.y = pk2(o[v][2] * r * g.z * silu(bflo(z.y)), o[v][3] * r * g.w * silu(bfhi(z.y)));
;         *(u32x2*)(proj + row * NCOL + CQH + hh * 128 + v0) = y; }
;     BAR_LDS();
.LBB0_643:
	s_or_b64 exec, exec, s[14:15]
	s_waitcnt lgkmcnt(0)
	s_barrier
	v_lshl_add_u32 v40, s4, 2, v196
	s_waitcnt lgkmcnt(0)
	ds_read2st64_b32 v[40:41], v40 offset1:1
	s_waitcnt vmcnt(9)
	v_lshlrev_b32_e32 v54, 16, v132
	v_and_b32_e32 v55, 0xffff0000, v132
	v_mul_f32_e32 v42, 0xbfb8aa3b, v54
	v_exp_f32_e32 v46, v42
	v_mul_f32_e32 v42, 0xbfb8aa3b, v55
	v_exp_f32_e32 v47, v42
	v_or_b32_e32 v50, s40, v122
	s_waitcnt lgkmcnt(0)
	v_add_f32_e32 v40, v40, v41
	v_lshl_add_u32 v41, v50, 2, 0
	v_fmamk_f32 v40, v40, 0x3c000000, v186
	v_add_u32_e32 v41, 0x1a800, v41
	v_add_f32_e32 v46, 1.0, v46
	v_rsq_f32_e32 v40, v40
	ds_read_b128 v[42:45], v41
	v_rcp_f32_e32 v56, v46
	v_add_f32_e32 v46, 1.0, v47
	v_rcp_f32_e32 v57, v46
	v_pk_mul_f32 v[36:37], v[36:37], v[40:41] op_sel_hi:[1,0]
	ds_read_b128 v[46:49], v41 offset:64
	s_waitcnt lgkmcnt(1)
	v_pk_mul_f32 v[36:37], v[42:43], v[36:37]
	v_pk_mul_f32 v[42:43], v[56:57], v[54:55]
	v_lshlrev_b32_e32 v54, 16, v133
	v_and_b32_e32 v55, 0xffff0000, v133
	v_mul_f32_e32 v51, 0xbfb8aa3b, v54
	v_mul_f32_e32 v56, 0xbfb8aa3b, v55
	v_exp_f32_e32 v51, v51
	v_exp_f32_e32 v56, v56
	v_pk_mul_f32 v[36:37], v[42:43], v[36:37]
	v_pk_mul_f32 v[38:39], v[38:39], v[40:41] op_sel_hi:[1,0]
	v_add_f32_e32 v42, 1.0, v51
	v_add_f32_e32 v43, 1.0, v56
	v_rcp_f32_e32 v42, v42
	v_rcp_f32_e32 v43, v43
	v_pk_mul_f32 v[38:39], v[44:45], v[38:39]
	v_cvt_pk_bf16_f32 v36, v36, v37
	s_lshl_b32 s4, s9, 7
	v_pk_mul_f32 v[42:43], v[42:43], v[54:55]
	s_lshl_b32 s6, s4, 1
	v_pk_mul_f32 v[38:39], v[42:43], v[38:39]
	v_lshl_add_u64 v[52:53], v[134:135], 0, s[6:7]
	v_cvt_pk_bf16_f32 v37, v38, v39
	s_waitcnt vmcnt(8)
	v_lshlrev_b32_e32 v38, 16, v130
	v_and_b32_e32 v39, 0xffff0000, v130
	v_mul_f32_e32 v42, 0xbfb8aa3b, v38
	v_exp_f32_e32 v44, v42
	v_mul_f32_e32 v42, 0xbfb8aa3b, v39
	v_exp_f32_e32 v45, v42
	v_ashrrev_i32_e32 v51, 31, v50
	v_add_f32_e32 v44, 1.0, v44
	v_rcp_f32_e32 v44, v44
	v_add_f32_e32 v45, 1.0, v45
	v_rcp_f32_e32 v45, v45
	v_lshlrev_b32_e32 v58, 1, v122
	v_mov_b32_e32 v59, 0
	v_or_b32_e32 v58, s40, v58
	v_lshl_add_u64 v[42:43], v[58:59], 1, v[52:53]
	v_mov_b64_e32 v[60:61], v[36:37]
	v_pk_mul_f32 v[32:33], v[32:33], v[40:41] op_sel_hi:[1,0]
	v_pk_mul_f32 v[36:37], v[44:45], v[38:39]
	v_lshlrev_b32_e32 v38, 16, v131
	v_and_b32_e32 v39, 0xffff0000, v131
	v_mul_f32_e32 v44, 0xbfb8aa3b, v38
	v_mul_f32_e32 v45, 0xbfb8aa3b, v39
	v_exp_f32_e32 v44, v44
	v_exp_f32_e32 v45, v45
	s_waitcnt lgkmcnt(0)
	v_pk_mul_f32 v[32:33], v[46:47], v[32:33]
	v_pk_mul_f32 v[34:35], v[34:35], v[40:41] op_sel_hi:[1,0]
	v_pk_mul_f32 v[32:33], v[36:37], v[32:33]
	v_add_f32_e32 v36, 1.0, v44
	v_add_f32_e32 v37, 1.0, v45
	v_rcp_f32_e32 v36, v36
	v_rcp_f32_e32 v37, v37
	v_pk_mul_f32 v[34:35], v[48:49], v[34:35]
	v_cvt_pk_bf16_f32 v32, v32, v33
	s_waitcnt vmcnt(7)
	v_lshlrev_b32_e32 v44, 16, v128
	v_pk_mul_f32 v[36:37], v[36:37], v[38:39]
	v_and_b32_e32 v45, 0xffff0000, v128
	v_pk_mul_f32 v[34:35], v[36:37], v[34:35]
	v_pk_mul_f32 v[28:29], v[28:29], v[40:41] op_sel_hi:[1,0]
	v_cvt_pk_bf16_f32 v33, v34, v35
	v_mov_b64_e32 v[62:63], v[32:33]
	global_store_dwordx4 v[42:43], v[60:63], off offset:1024
	v_mul_f32_e32 v32, 0xbfb8aa3b, v44
	v_exp_f32_e32 v36, v32
	v_mul_f32_e32 v32, 0xbfb8aa3b, v45
	v_exp_f32_e32 v37, v32
	ds_read_b128 v[32:35], v41 offset:128
	v_add_f32_e32 v36, 1.0, v36
	v_rcp_f32_e32 v46, v36
	v_add_f32_e32 v36, 1.0, v37
	v_rcp_f32_e32 v47, v36
	ds_read_b128 v[36:39], v41 offset:192
	s_waitcnt lgkmcnt(1)
	v_pk_mul_f32 v[28:29], v[28:29], v[32:33]
	s_waitcnt vmcnt(5)
	v_mov_b64_e32 v[74:75], v[10:11]
	v_pk_mul_f32 v[32:33], v[46:47], v[44:45]
	v_lshlrev_b32_e32 v44, 16, v129
	v_and_b32_e32 v45, 0xffff0000, v129
	v_mul_f32_e32 v41, 0xbfb8aa3b, v44
	v_mul_f32_e32 v46, 0xbfb8aa3b, v45
	v_exp_f32_e32 v41, v41
	v_exp_f32_e32 v46, v46
	v_pk_mul_f32 v[28:29], v[32:33], v[28:29]
	s_waitcnt vmcnt(4)
	v_mov_b64_e32 v[102:103], v[14:15]
	v_add_f32_e32 v32, 1.0, v41
	v_add_f32_e32 v33, 1.0, v46
	v_rcp_f32_e32 v32, v32
	v_rcp_f32_e32 v33, v33
	v_pk_mul_f32 v[30:31], v[30:31], v[40:41] op_sel_hi:[1,0]
	v_cvt_pk_bf16_f32 v28, v28, v29
	v_pk_mul_f32 v[30:31], v[30:31], v[34:35]
	v_pk_mul_f32 v[32:33], v[32:33], v[44:45]
	v_pk_mul_f32 v[24:25], v[24:25], v[40:41] op_sel_hi:[1,0]
	v_pk_mul_f32 v[30:31], v[32:33], v[30:31]
	v_lshlrev_b32_e32 v32, 16, v126
	v_and_b32_e32 v33, 0xffff0000, v126
	v_mul_f32_e32 v29, 0xbfb8aa3b, v32
	v_exp_f32_e32 v34, v29
	v_mul_f32_e32 v29, 0xbfb8aa3b, v33
	v_exp_f32_e32 v35, v29
	v_cvt_pk_bf16_f32 v29, v30, v31
	v_add_f32_e32 v30, 1.0, v34
	v_rcp_f32_e32 v30, v30
	v_add_f32_e32 v31, 1.0, v35
	v_rcp_f32_e32 v31, v31
	v_mov_b64_e32 v[64:65], v[28:29]
	s_waitcnt lgkmcnt(0)
	v_pk_mul_f32 v[24:25], v[24:25], v[36:37]
	v_pk_mul_f32 v[26:27], v[26:27], v[40:41] op_sel_hi:[1,0]
	v_pk_mul_f32 v[28:29], v[30:31], v[32:33]
	v_lshlrev_b32_e32 v30, 16, v127
	v_and_b32_e32 v31, 0xffff0000, v127
	v_mul_f32_e32 v32, 0xbfb8aa3b, v30
	v_mul_f32_e32 v33, 0xbfb8aa3b, v31
	v_exp_f32_e32 v32, v32
	v_exp_f32_e32 v33, v33
	v_pk_mul_f32 v[24:25], v[28:29], v[24:25]
	v_pk_mul_f32 v[26:27], v[26:27], v[38:39]
	v_add_f32_e32 v28, 1.0, v32
	v_add_f32_e32 v29, 1.0, v33
	v_rcp_f32_e32 v28, v28
	v_rcp_f32_e32 v29, v29
	v_cvt_pk_bf16_f32 v24, v24, v25
	s_andn2_b64 vcc, exec, s[70:71]
	v_mov_b64_e32 v[72:73], v[8:9]
	v_pk_mul_f32 v[28:29], v[28:29], v[30:31]
	v_mov_b64_e32 v[100:101], v[12:13]
	v_pk_mul_f32 v[26:27], v[28:29], v[26:27]
	s_waitcnt vmcnt(1)
	v_mov_b64_e32 v[30:31], v[22:23]
	v_cvt_pk_bf16_f32 v25, v26, v27
	v_mov_b64_e32 v[66:67], v[24:25]
	global_store_dwordx4 v[42:43], v[64:67], off offset:1088
	s_waitcnt lgkmcnt(0)
	s_barrier
	v_mov_b64_e32 v[26:27], v[18:19]
	v_mov_b64_e32 v[24:25], v[16:17]
	v_mov_b64_e32 v[28:29], v[20:21]
	s_cbranch_vccz .LBB0_679
